# attention: paired waves (32 queries x one q/k component per wave), K fragments shared by two query sub-blocks, uniform pipelined loop incl. masked diagonal tiles, accumulator swap through LDS before t
# baseline (speedup 1.0000x reference)
; #define LAS __attribute__((address_space(3)))
; __device__ __forceinline__ int my_tid() { int t = threadIdx.x; asm volatile("" : "+v"(t)); return t; }
; #define ATT_LOAD(tile) do { _Pragma("unroll") for (int i = 0; i < 2; ++i) { kr[i] = *(const u32x4*)(kg + (size_t)(64 * (tile) + 32 * i) * PP); vr[i] = *(const u32x4*)(vg + (size_t)(64 * (tile) + 32 * i) * PP); } } while (0)
; #define ATT_STORE(buf) do { LAS char* nb_ = lds + (buf) * ABUF; _Pragma("unroll") for (int i = 0; i < 2; ++i) { *(LAS u32x4*)(nb_ + soff + 32 * i * APIT) = kr[i]; *(LAS u32x4*)(nb_ + ATILE + soff + 32 * i * APIT) = vr[i]; } } while (0)
; __device__ __forceinline__ void attn_item(LAS char* lds, bf16_t* proj, int bl, int h, int qb, float lam, float oscale, const float* gdh, float smax) {
;     const int tid = my_tid(), lane = tid & 63, wid = __builtin_amdgcn_readfirstlane(tid >> 6), g = lane >> 4, fr = lane & 15;
;     const size_t rowbase = (size_t)bl * SEQ; const int q0 = qb * 128, qpos = q0 + 16 * wid + fr;
;     bf16_t* qp = proj + SEC(C_AQ) + (rowbase + qpos) * PP + h * 128;
;     bf16x8 qf[2][2];
; #pragma unroll
;     for (int c = 0; c < 2; ++c)
; #pragma unroll
;         for (int ks = 0; ks < 2; ++ks) qf[c][ks] = *(const bf16x8*)(qp + c * 64 + 32 * ks + 8 * g);
;     f32x4 O[2][8], Oe[2];
; #pragma unroll
;     for (int c = 0; c < 2; ++c) { Oe[c] = (f32x4){0.f, 0.f, 0.f, 0.f};
; #pragma unroll
;         for (int nb = 0; nb < 8; ++nb) O[c][nb] = (f32x4){0.f, 0.f, 0.f, 0.f}; }
;     const f32x4 negM = (f32x4){-smax, -smax, -smax, -smax};
;     const short one16 = (fr == 0) ? (short)0x3F80 : (short)0;
;     const bf16x8 onesf = (bf16x8){one16, one16, one16, one16, one16, one16, one16, one16};
;     const int NT = 2 * (qb + 1);
;     const int sr0 = tid >> 4, sc = tid & 15;
;     const bf16_t* kg = proj + SEC(C_AK) + (rowbase + sr0) * PP + h * 128 + sc * 8;
;     const bf16_t* vg = proj + SEC(C_AV) + (rowbase + sr0) * PP + h * 128 + sc * 8;
;     const int soff = sr0 * APIT + sc * 16;
;     u32x4 kr[2], vr[2];
;     ...
;     ATT_LOAD(0); ATT_STORE(0);
;     __syncthreads();
;     const int qmaxw = q0 + 16 * wid + 15;
;     int t = 0;
.LBB0_241:
	s_and_b32 s0, s40, 7
	s_lshl_b32 s44, s0, 8
	s_bfe_u32 s0, s41, 0x50003
	s_and_b32 s42, s41, 7
	s_and_b32 s1, s41, 0x100
	s_xor_b32 s4, s0, 31
	s_cmp_eq_u32 s1, 0
	v_mov_b32_e32 v14, v194
	s_cselect_b32 s45, s0, s4
	s_lshl_b32 s46, s45, 7
	v_readfirstlane_b32 s4, v14
	s_ashr_i32 s4, s4, 2
	s_and_b32 s43, s4, -16
	s_ashr_i32 s36, s41, 8
	v_and_b32_e32 v176, 15, v14
	s_add_i32 s43, s43, s46
	s_ashr_i32 s37, s36, 31
	v_or_b32_e32 v164, s43, v176
	s_lshl_b64 s[0:1], s[36:37], 12
	v_ashrrev_i32_e32 v165, 31, v164
	v_lshl_add_u64 v[162:163], s[0:1], 0, v[164:165]
	v_readlane_b32 s4, v252, 28
	v_lshlrev_b64 v[6:7], 11, v[162:163]
	v_readlane_b32 s5, v252, 29
	s_lshl_b32 s84, s42, 8
	v_lshlrev_b32_e32 v0, 4, v176
	v_lshl_add_u64 v[6:7], s[4:5], 0, v[6:7]
	v_lshl_add_u64 v[8:9], v[6:7], 0, s[84:85]
	v_ashrrev_i32_e32 v6, 4, v14
	v_ashrrev_i32_e32 v7, 31, v6
	v_lshl_add_u64 v[10:11], s[0:1], 0, v[6:7]
	v_readlane_b32 s0, v252, 30
	v_lshlrev_b64 v[10:11], 11, v[10:11]
	v_readlane_b32 s1, v252, 31
	v_and_b32_e32 v166, 48, v14
	v_mov_b32_e32 v167, v1
	v_lshl_add_u64 v[12:13], s[0:1], 0, v[10:11]
	v_readlane_b32 s0, v252, 32
	v_readlane_b32 s1, v252, 33
	v_lshl_add_u64 v[12:13], v[12:13], 0, s[84:85]
	v_lshl_add_u64 v[12:13], v[12:13], 0, v[0:1]
	v_lshl_add_u64 v[10:11], s[0:1], 0, v[10:11]
	v_lshl_add_u64 v[10:11], v[10:11], 0, s[84:85]
	s_mov_b32 s0, 0x10000
	v_lshl_add_u64 v[10:11], v[10:11], 0, v[0:1]
	global_load_dwordx4 v[118:121], v[12:13], off
	global_load_dwordx4 v[114:117], v[10:11], off
	v_add_co_u32_e32 v12, vcc, s0, v12
	v_lshl_add_u64 v[8:9], v[8:9], 0, v[166:167]
	s_nop 0
	v_addc_co_u32_e32 v13, vcc, 0, v13, vcc
	v_add_co_u32_e32 v10, vcc, s0, v10
	s_movk_i32 s0, 0x120
	s_nop 0
	v_addc_co_u32_e32 v11, vcc, 0, v11, vcc
	global_load_dwordx4 v[122:125], v[12:13], off
	global_load_dwordx4 v[126:129], v[10:11], off
	global_load_dwordx4 v[34:37], v[8:9], off
	global_load_dwordx4 v[38:41], v[8:9], off offset:64
	global_load_dwordx4 v[42:45], v[8:9], off offset:128
	global_load_dwordx4 v[50:53], v[8:9], off offset:192
	v_cmp_eq_u32_e32 vcc, 0, v176
	v_mov_b32_e32 v11, 0x3f80
	v_and_b32_e32 v8, 63, v14
	v_cndmask_b32_e32 v11, 0, v11, vcc
	v_mul_lo_u32 v12, v6, s0
	s_mov_b32 s0, 0x5040100
	v_bfe_u32 v9, v14, 2, 4
	v_lshlrev_b32_e32 v10, 3, v14
	v_or_b32_e32 v8, 48, v8
	v_perm_b32 v74, v11, v11, s0
	v_mul_u32_u24_e32 v167, 0x120, v176
	v_and_b32_e32 v165, 12, v9
	v_mul_u32_u24_e32 v177, 0x120, v9
	v_and_b32_e32 v178, 24, v10
	v_add3_u32 v179, v12, v0, 0
	v_mul_u32_u24_e32 v180, 0x120, v8
	v_mov_b32_e32 v75, v74
	v_mov_b32_e32 v76, v74
	v_mov_b32_e32 v77, v74
	s_cmp_lg_u32 s45, 0
	v_lshlrev_b64 v[170:171], 11, v[6:7]
	s_waitcnt vmcnt(7)
	ds_write_b128 v179, v[118:121]
	s_waitcnt vmcnt(6)
	ds_write_b128 v179, v[114:117] offset:18432
	s_waitcnt vmcnt(5)
	ds_write_b128 v179, v[122:125] offset:9216
	s_waitcnt vmcnt(4)
	ds_write_b128 v179, v[126:129] offset:27648
	s_waitcnt lgkmcnt(0)
	s_barrier
	s_lshl_b64 s[38:39], s[36:37], 23
	v_lshlrev_b64 v[168:169], 11, v[6:7]
	v_lshl_add_u64 v[6:7], s[38:39], 0, v[168:169]
	v_or_b32_e32 v6, s44, v6
	v_readlane_b32 s0, v254, 29
	v_lshl_add_u64 v[6:7], v[6:7], 0, v[0:1]
	v_readlane_b32 s1, v254, 30
	v_mov_b32_e32 v86, 0
	s_mov_b32 s47, 0
	v_lshl_add_u64 v[172:173], s[0:1], 0, v[6:7]
	s_mov_b32 s48, 1
	v_mov_b32_e32 v87, v86
	v_mov_b32_e32 v88, v86
	v_mov_b32_e32 v89, v86
	v_mov_b32_e32 v66, v86
	v_mov_b32_e32 v67, v86
	v_mov_b32_e32 v68, v86
	v_mov_b32_e32 v69, v86
	v_mov_b32_e32 v10, v86
	v_mov_b32_e32 v11, v86
	v_mov_b32_e32 v12, v86
	v_mov_b32_e32 v13, v86
	v_mov_b32_e32 v6, v86
	v_mov_b32_e32 v7, v86
	v_mov_b32_e32 v8, v86
	v_mov_b32_e32 v9, v86
	v_mov_b32_e32 v14, v86
	v_mov_b32_e32 v15, v86
	v_mov_b32_e32 v16, v86
	v_mov_b32_e32 v17, v86
	v_mov_b32_e32 v18, v86
	v_mov_b32_e32 v19, v86
	v_mov_b32_e32 v20, v86
	v_mov_b32_e32 v21, v86
	v_mov_b32_e32 v22, v86
	v_mov_b32_e32 v23, v86
	v_mov_b32_e32 v24, v86
	v_mov_b32_e32 v25, v86
	v_mov_b32_e32 v26, v86
	v_mov_b32_e32 v27, v86
	v_mov_b32_e32 v28, v86
	v_mov_b32_e32 v29, v86
	v_mov_b32_e32 v30, v86
	v_mov_b32_e32 v31, v86
	v_mov_b32_e32 v32, v86
	v_mov_b32_e32 v33, v86
	v_mov_b32_e32 v46, v86
	v_mov_b32_e32 v47, v86
	v_mov_b32_e32 v48, v86
	v_mov_b32_e32 v49, v86
	v_mov_b32_e32 v54, v86
	v_mov_b32_e32 v55, v86
	v_mov_b32_e32 v56, v86
	v_mov_b32_e32 v57, v86
	v_mov_b32_e32 v58, v86
	v_mov_b32_e32 v59, v86
	v_mov_b32_e32 v60, v86
	v_mov_b32_e32 v61, v86
	v_mov_b32_e32 v62, v86
	v_mov_b32_e32 v63, v86
	v_mov_b32_e32 v64, v86
	v_mov_b32_e32 v65, v86
	v_mov_b32_e32 v70, v86
	v_mov_b32_e32 v71, v86
	v_mov_b32_e32 v72, v86
	v_mov_b32_e32 v73, v86
	v_mov_b32_e32 v78, v86
	v_mov_b32_e32 v79, v86
	v_mov_b32_e32 v80, v86
	v_mov_b32_e32 v81, v86
	v_mov_b32_e32 v90, v86
	v_mov_b32_e32 v91, v86
	v_mov_b32_e32 v92, v86
	v_mov_b32_e32 v93, v86
	v_mov_b32_e32 v94, v86
	v_mov_b32_e32 v95, v86
	v_mov_b32_e32 v96, v86
	v_mov_b32_e32 v97, v86
	v_mov_b32_e32 v82, v86
	v_mov_b32_e32 v83, v86
	v_mov_b32_e32 v84, v86
	v_mov_b32_e32 v85, v86
	v_readfirstlane_b32 s0, v194
	s_nop 3
	s_lshr_b32 s0, s0, 6
	s_and_b32 s48, s0, 1
	s_lshr_b32 s1, s0, 1
	s_lshl_b32 s1, s1, 5
	v_lshrrev_b32_e32 v243, 2, v166
	v_sub_u32_e32 v243, v176, v243
	v_add_u32_e32 v243, s1, v243
	s_lshl_b32 s1, s48, 7
	v_add_u32_e32 v230, v166, v167
	v_add_u32_e32 v230, s1, v230
	v_add_u32_e32 v231, v177, v178
	s_mov_b32 s4, 0xfdff0000
	s_mov_b32 s5, -1
	s_mov_b32 s6, 0xfe000000
	s_mov_b32 s7, -1
	s_mov_b32 s8, 0xfffd0000
	s_mov_b32 s9, -1
	s_mov_b32 s10, 0xfffe0000
	s_mov_b32 s11, -1
	v_readlane_b32 s12, v252, 28
	v_readlane_b32 s13, v252, 29
	s_mul_i32 s14, s48, 0xffff8080
	s_ashr_i32 s15, s14, 31
	s_add_u32 s12, s12, s14
	s_addc_u32 s13, s13, s15
	s_add_u32 s12, s12, s84
	s_addc_u32 s13, s13, 0
	v_lshlrev_b64 v[240:241], 11, v[162:163]
	v_mov_b32_e32 v238, v166
	v_mov_b32_e32 v239, 0
	v_lshl_add_u64 v[240:241], v[240:241], 0, v[238:239]
	v_lshl_add_u64 v[240:241], v[240:241], 0, s[12:13]
	global_load_dwordx4 v[34:37], v[240:241], off
	global_load_dwordx4 v[38:41], v[240:241], off offset:64
	s_mov_b32 s12, 0x8000
	s_mov_b32 s13, 0
	v_lshl_add_u64 v[240:241], v[240:241], 0, s[12:13]
	global_load_dwordx4 v[42:45], v[240:241], off
	global_load_dwordx4 v[50:53], v[240:241], off offset:64
	s_cmp_eq_u32 s45, 0
	s_cbranch_scc1 .Lmy_pre_masked
; #define LAS __attribute__((address_space(3)))
; __device__ __forceinline__ f32x4 mfma16(bf16x8 a, bf16x8 b, f32x4 c) { return __builtin_amdgcn_mfma_f32_16x16x32_bf16(a, b, c, 0, 0, 0); }
; __device__ __forceinline__ void attn_step_fast(const LAS char* Kb, const LAS char* Vb, int lane, const bf16x8 (&qf)[2][2], const f32x4 negM, const bf16x8 onesf, f32x4 (&O)[2][8], f32x4 (&Oe)[2]) {
;     f32x4 s0[4], s1[4];
;     bf16x8 p0[2], p1[2];
;     {
;         bf16x8 kf[2][4][2];
; #pragma unroll
;         for (int c = 0; c < 2; ++c)
; #pragma unroll
;             for (int kb = 0; kb < 4; ++kb)
; #pragma unroll
;                 for (int ks = 0; ks < 2; ++ks) kf[c][kb][ks] = rowfrag(Kb, APIT, 16 * kb, c * 64 + 32 * ks, lane);
;         __builtin_amdgcn_sched_barrier(0);
; #pragma unroll
;         for (int kb = 0; kb < 4; ++kb) s0[kb] = mfma16(kf[0][kb][0], qf[0][0], negM);
; #pragma unroll
;         for (int kb = 0; kb < 4; ++kb) s0[kb] = mfma16(kf[0][kb][1], qf[0][1], s0[kb]);
;         __builtin_amdgcn_sched_barrier(0);
; #pragma unroll
;         for (int kb = 0; kb < 4; ++kb) s1[kb] = mfma16(kf[1][kb][0], qf[1][0], negM);
; #pragma unroll
;         for (int kb = 0; kb < 4; ++kb) s1[kb] = mfma16(kf[1][kb][1], qf[1][1], s1[kb]);
;     }
;     ...
;     ATT_EXPPACK(s0, p0);
	s_mov_b32 s49, 0
	s_mov_b32 s50, 0x9000
	v_add_u32_e32 v181, s49, v230
	ds_read_b128 v[206:209], v181
	ds_read_b128 v[210:213], v181 offset:64
	ds_read_b128 v[214:217], v181 offset:4608
	ds_read_b128 v[218:221], v181 offset:4672
	ds_read_b128 v[222:225], v181 offset:9216
	v_lshl_add_u64 v[240:241], v[172:173], 0, s[4:5]
	global_load_dwordx4 v[146:149], v[240:241], off
	v_lshl_add_u64 v[240:241], v[172:173], 0, s[6:7]
	global_load_dwordx4 v[150:153], v[240:241], off
	v_lshl_add_u64 v[172:173], v[172:173], 0, s[76:77]
	s_waitcnt vmcnt(2)
	s_waitcnt lgkmcnt(4)
	v_mfma_f32_16x16x32_bf16 v[98:101], v[206:209], v[34:37], v[2:5]
	v_mfma_f32_16x16x32_bf16 v[114:117], v[206:209], v[42:45], v[2:5]
	ds_read_b128 v[206:209], v181 offset:9280
	s_waitcnt lgkmcnt(4)
	v_mfma_f32_16x16x32_bf16 v[98:101], v[210:213], v[38:41], v[98:101]
	v_mfma_f32_16x16x32_bf16 v[114:117], v[210:213], v[50:53], v[114:117]
	ds_read_b128 v[210:213], v181 offset:13824
	s_waitcnt lgkmcnt(4)
	v_mfma_f32_16x16x32_bf16 v[102:105], v[214:217], v[34:37], v[2:5]
	v_mfma_f32_16x16x32_bf16 v[118:121], v[214:217], v[42:45], v[2:5]
	ds_read_b128 v[214:217], v181 offset:13888
	s_waitcnt lgkmcnt(4)
	v_mfma_f32_16x16x32_bf16 v[102:105], v[218:221], v[38:41], v[102:105]
	v_mfma_f32_16x16x32_bf16 v[118:121], v[218:221], v[50:53], v[118:121]
	s_waitcnt lgkmcnt(3)
	v_mfma_f32_16x16x32_bf16 v[106:109], v[222:225], v[34:37], v[2:5]
	v_mfma_f32_16x16x32_bf16 v[122:125], v[222:225], v[42:45], v[2:5]
	s_waitcnt lgkmcnt(2)
	v_mfma_f32_16x16x32_bf16 v[106:109], v[206:209], v[38:41], v[106:109]
	v_mfma_f32_16x16x32_bf16 v[122:125], v[206:209], v[50:53], v[122:125]
	s_waitcnt lgkmcnt(1)
	v_mfma_f32_16x16x32_bf16 v[110:113], v[210:213], v[34:37], v[2:5]
	v_mfma_f32_16x16x32_bf16 v[126:129], v[210:213], v[42:45], v[2:5]
	s_waitcnt lgkmcnt(0)
	v_mfma_f32_16x16x32_bf16 v[110:113], v[214:217], v[38:41], v[110:113]
	v_mfma_f32_16x16x32_bf16 v[126:129], v[214:217], v[50:53], v[126:129]
	v_add_u32_e32 v238, s50, v179
	s_nop 7
	v_exp_f32_e32 v98, v98
	v_exp_f32_e32 v99, v99
	v_exp_f32_e32 v100, v100
	v_exp_f32_e32 v101, v101
	v_exp_f32_e32 v114, v114
	v_exp_f32_e32 v115, v115
	v_exp_f32_e32 v116, v116
	v_exp_f32_e32 v117, v117
	v_exp_f32_e32 v102, v102
	v_exp_f32_e32 v103, v103
	v_exp_f32_e32 v104, v104
	v_exp_f32_e32 v105, v105
	v_exp_f32_e32 v118, v118
	v_exp_f32_e32 v119, v119
	v_exp_f32_e32 v120, v120
	v_exp_f32_e32 v121, v121
	v_exp_f32_e32 v106, v106
	v_exp_f32_e32 v107, v107
	v_exp_f32_e32 v108, v108
	v_exp_f32_e32 v109, v109
	v_exp_f32_e32 v122, v122
	v_exp_f32_e32 v123, v123
	v_exp_f32_e32 v124, v124
	v_exp_f32_e32 v125, v125
	v_exp_f32_e32 v110, v110
	v_exp_f32_e32 v111, v111
	v_exp_f32_e32 v112, v112
	v_exp_f32_e32 v113, v113
	v_exp_f32_e32 v126, v126
	v_exp_f32_e32 v127, v127
	v_exp_f32_e32 v128, v128
	v_exp_f32_e32 v129, v129
	v_cvt_pk_bf16_f32 v130, v98, v99
	v_cvt_pk_bf16_f32 v131, v100, v101
	v_cvt_pk_bf16_f32 v132, v102, v103
	v_cvt_pk_bf16_f32 v133, v104, v105
	v_cvt_pk_bf16_f32 v138, v114, v115
	v_cvt_pk_bf16_f32 v139, v116, v117
	v_cvt_pk_bf16_f32 v140, v118, v119
	v_cvt_pk_bf16_f32 v141, v120, v121
	s_waitcnt vmcnt(1)
	ds_write_b128 v238, v[146:149]
	s_waitcnt vmcnt(0)
	ds_write_b128 v238, v[150:153] offset:9216
	s_waitcnt lgkmcnt(0)
	s_barrier
	s_branch .Lmy_pre_done
.Lmy_pre_masked:
	s_mov_b32 s49, 0
	s_mov_b32 s50, 0x9000
	v_add_u32_e32 v181, s49, v230
	ds_read_b128 v[206:209], v181
	ds_read_b128 v[210:213], v181 offset:64
	ds_read_b128 v[214:217], v181 offset:4608
	ds_read_b128 v[218:221], v181 offset:4672
	ds_read_b128 v[222:225], v181 offset:9216
	v_lshl_add_u64 v[240:241], v[172:173], 0, s[4:5]
	global_load_dwordx4 v[146:149], v[240:241], off
	v_lshl_add_u64 v[240:241], v[172:173], 0, s[6:7]
	global_load_dwordx4 v[150:153], v[240:241], off
	v_lshl_add_u64 v[172:173], v[172:173], 0, s[76:77]
	s_waitcnt vmcnt(2)
	s_waitcnt lgkmcnt(4)
	v_mfma_f32_16x16x32_bf16 v[98:101], v[206:209], v[34:37], v[2:5]
	v_mfma_f32_16x16x32_bf16 v[114:117], v[206:209], v[42:45], v[2:5]
	ds_read_b128 v[206:209], v181 offset:9280
	s_waitcnt lgkmcnt(4)
	v_mfma_f32_16x16x32_bf16 v[98:101], v[210:213], v[38:41], v[98:101]
	v_mfma_f32_16x16x32_bf16 v[114:117], v[210:213], v[50:53], v[114:117]
	ds_read_b128 v[210:213], v181 offset:13824
	s_waitcnt lgkmcnt(4)
	v_mfma_f32_16x16x32_bf16 v[102:105], v[214:217], v[34:37], v[2:5]
	v_mfma_f32_16x16x32_bf16 v[118:121], v[214:217], v[42:45], v[2:5]
	ds_read_b128 v[214:217], v181 offset:13888
	s_waitcnt lgkmcnt(4)
	v_mfma_f32_16x16x32_bf16 v[102:105], v[218:221], v[38:41], v[102:105]
	v_mfma_f32_16x16x32_bf16 v[118:121], v[218:221], v[50:53], v[118:121]
	s_waitcnt lgkmcnt(3)
	v_mfma_f32_16x16x32_bf16 v[106:109], v[222:225], v[34:37], v[2:5]
	v_mfma_f32_16x16x32_bf16 v[122:125], v[222:225], v[42:45], v[2:5]
	s_waitcnt lgkmcnt(2)
	v_mfma_f32_16x16x32_bf16 v[106:109], v[206:209], v[38:41], v[106:109]
	v_mfma_f32_16x16x32_bf16 v[122:125], v[206:209], v[50:53], v[122:125]
	s_waitcnt lgkmcnt(1)
	v_mfma_f32_16x16x32_bf16 v[110:113], v[210:213], v[34:37], v[2:5]
	v_mfma_f32_16x16x32_bf16 v[126:129], v[210:213], v[42:45], v[2:5]
	s_waitcnt lgkmcnt(0)
; __device__ __forceinline__ unsigned cvt_pk_bf16(float lo, float hi) { const f32x2_t v = {lo, hi}; const bf16x2_t b = __builtin_convertvector(v, bf16x2_t); return __builtin_bit_cast(unsigned, b); }
; __device__ __forceinline__ void attn_qkexp(const LAS char* Kb, int k0, int q0, int wid, int lane, int g, int qpos, const bf16x8 (&qf)[2][2], const f32x4 negM, bf16x8 (&pf)[2][2]) {
;     ...
;     if (k0 + 63 > q0 + 16 * wid) {
; #pragma unroll
;         for (int c = 0; c < 2; ++c)
; #pragma unroll
;             for (int kb = 0; kb < 4; ++kb)
; #pragma unroll
;                 for (int r = 0; r < 4; ++r) if (k0 + 16 * kb + 4 * g + r > qpos) s[c][kb][r] = -INFINITY;
;     }
; #pragma unroll
;     for (int c = 0; c < 2; ++c) {
; #pragma unroll
;         for (int kb = 0; kb < 4; ++kb)
; #pragma unroll
;             for (int r = 0; r < 4; ++r) s[c][kb][r] = __builtin_amdgcn_exp2f(s[c][kb][r]);
; #pragma unroll
;         for (int tt = 0; tt < 2; ++tt) { u32x4 w; w.x = cvt_pk_bf16(s[c][2 * tt][0], s[c][2 * tt][1]); w.y = cvt_pk_bf16(s[c][2 * tt][2], s[c][2 * tt][3]);
;             w.z = cvt_pk_bf16(s[c][2 * tt + 1][0], s[c][2 * tt + 1][1]); w.w = cvt_pk_bf16(s[c][2 * tt + 1][2], s[c][2 * tt + 1][3]); pf[c][tt] = __builtin_bit_cast(bf16x8, w); }
;     }
	v_mfma_f32_16x16x32_bf16 v[110:113], v[214:217], v[38:41], v[110:113]
	v_mfma_f32_16x16x32_bf16 v[126:129], v[214:217], v[50:53], v[126:129]
	v_add_u32_e32 v238, s50, v179
	s_nop 7
	v_add_u32_e32 v240, 0, v243
	v_add_u32_e32 v241, 16, v243
	v_cmp_gt_i32_e64 s[12:13], 0, v240
	v_cmp_gt_i32_e64 s[14:15], 1, v240
	v_cmp_gt_i32_e64 s[16:17], 2, v240
	v_cmp_gt_i32_e64 s[18:19], 3, v240
	v_cndmask_b32_e64 v98, v98, v236, s[12:13]
	v_cmp_gt_i32_e64 s[20:21], 16, v240
	v_cndmask_b32_e64 v99, v99, v236, s[14:15]
	v_cmp_gt_i32_e64 s[22:23], 17, v240
	v_cndmask_b32_e64 v100, v100, v236, s[16:17]
	v_cmp_gt_i32_e64 s[24:25], 18, v240
	v_cndmask_b32_e64 v101, v101, v236, s[18:19]
	v_cmp_gt_i32_e64 s[26:27], 19, v240
	v_cndmask_b32_e64 v102, v102, v236, s[20:21]
	v_cmp_gt_i32_e64 s[28:29], 32, v240
	v_cndmask_b32_e64 v103, v103, v236, s[22:23]
	v_cmp_gt_i32_e64 s[30:31], 33, v240
	v_cndmask_b32_e64 v104, v104, v236, s[24:25]
	v_cmp_gt_i32_e64 s[12:13], 34, v240
	v_cndmask_b32_e64 v105, v105, v236, s[26:27]
	v_cmp_gt_i32_e64 s[14:15], 35, v240
	v_cndmask_b32_e64 v106, v106, v236, s[28:29]
	v_cmp_gt_i32_e64 s[16:17], 48, v240
	v_cndmask_b32_e64 v107, v107, v236, s[30:31]
	v_cmp_gt_i32_e64 s[18:19], 49, v240
	v_cndmask_b32_e64 v108, v108, v236, s[12:13]
	v_cmp_gt_i32_e64 s[20:21], 50, v240
	v_cndmask_b32_e64 v109, v109, v236, s[14:15]
	v_cmp_gt_i32_e64 s[22:23], 51, v240
	v_cndmask_b32_e64 v110, v110, v236, s[16:17]
	v_cmp_gt_i32_e64 s[24:25], 0, v241
	v_cndmask_b32_e64 v111, v111, v236, s[18:19]
	v_cmp_gt_i32_e64 s[26:27], 1, v241
	v_cndmask_b32_e64 v112, v112, v236, s[20:21]
	v_cmp_gt_i32_e64 s[28:29], 2, v241
	v_cndmask_b32_e64 v113, v113, v236, s[22:23]
	v_cmp_gt_i32_e64 s[30:31], 3, v241
	v_cndmask_b32_e64 v114, v114, v236, s[24:25]
	v_cmp_gt_i32_e64 s[12:13], 16, v241
	v_cndmask_b32_e64 v115, v115, v236, s[26:27]
	v_cmp_gt_i32_e64 s[14:15], 17, v241
	v_cndmask_b32_e64 v116, v116, v236, s[28:29]
	v_cmp_gt_i32_e64 s[16:17], 18, v241
	v_cndmask_b32_e64 v117, v117, v236, s[30:31]
	v_cmp_gt_i32_e64 s[18:19], 19, v241
	v_cndmask_b32_e64 v118, v118, v236, s[12:13]
	v_cmp_gt_i32_e64 s[20:21], 32, v241
	v_cndmask_b32_e64 v119, v119, v236, s[14:15]
	v_cmp_gt_i32_e64 s[22:23], 33, v241
	v_cndmask_b32_e64 v120, v120, v236, s[16:17]
	v_cmp_gt_i32_e64 s[24:25], 34, v241
	v_cndmask_b32_e64 v121, v121, v236, s[18:19]
	v_cmp_gt_i32_e64 s[26:27], 35, v241
	v_cndmask_b32_e64 v122, v122, v236, s[20:21]
	v_cmp_gt_i32_e64 s[28:29], 48, v241
	v_cndmask_b32_e64 v123, v123, v236, s[22:23]
	v_cmp_gt_i32_e64 s[30:31], 49, v241
	v_cndmask_b32_e64 v124, v124, v236, s[24:25]
	v_cmp_gt_i32_e64 s[12:13], 50, v241
	v_cndmask_b32_e64 v125, v125, v236, s[26:27]
	v_cmp_gt_i32_e64 s[14:15], 51, v241
	v_cndmask_b32_e64 v126, v126, v236, s[28:29]
	s_nop 1
	v_cndmask_b32_e64 v127, v127, v236, s[30:31]
	v_cndmask_b32_e64 v128, v128, v236, s[12:13]
	v_cndmask_b32_e64 v129, v129, v236, s[14:15]
	v_exp_f32_e32 v98, v98
	v_exp_f32_e32 v99, v99
	v_exp_f32_e32 v100, v100
	v_exp_f32_e32 v101, v101
	v_exp_f32_e32 v114, v114
	v_exp_f32_e32 v115, v115
	v_exp_f32_e32 v116, v116
	v_exp_f32_e32 v117, v117
	v_exp_f32_e32 v102, v102
	v_exp_f32_e32 v103, v103
	v_exp_f32_e32 v104, v104
	v_exp_f32_e32 v105, v105
	v_exp_f32_e32 v118, v118
	v_exp_f32_e32 v119, v119
	v_exp_f32_e32 v120, v120
	v_exp_f32_e32 v121, v121
	v_exp_f32_e32 v106, v106
	v_exp_f32_e32 v107, v107
	v_exp_f32_e32 v108, v108
	v_exp_f32_e32 v109, v109
	v_exp_f32_e32 v122, v122
	v_exp_f32_e32 v123, v123
	v_exp_f32_e32 v124, v124
	v_exp_f32_e32 v125, v125
	v_exp_f32_e32 v110, v110
	v_exp_f32_e32 v111, v111
	v_exp_f32_e32 v112, v112
	v_exp_f32_e32 v113, v113
	v_exp_f32_e32 v126, v126
	v_exp_f32_e32 v127, v127
	v_exp_f32_e32 v128, v128
	v_exp_f32_e32 v129, v129
	v_cvt_pk_bf16_f32 v130, v98, v99
	v_cvt_pk_bf16_f32 v131, v100, v101
	v_cvt_pk_bf16_f32 v132, v102, v103
	v_cvt_pk_bf16_f32 v133, v104, v105
	v_cvt_pk_bf16_f32 v138, v114, v115
	v_cvt_pk_bf16_f32 v139, v116, v117
	v_cvt_pk_bf16_f32 v140, v118, v119
	v_cvt_pk_bf16_f32 v141, v120, v121
	s_waitcnt vmcnt(1)
	ds_write_b128 v238, v[146:149]
	s_waitcnt vmcnt(0)
	ds_write_b128 v238, v[150:153] offset:9216
	s_waitcnt lgkmcnt(0)
	s_barrier
.Lmy_pre_done:
	s_lshl_b32 s47, s45, 1
	s_mov_b32 s49, 0x9000
	s_mov_b32 s50, 0
	s_cmp_eq_u32 s47, 0
	s_cbranch_scc1 .Lmy_attn_last
; #define LAS __attribute__((address_space(3)))
; __device__ __forceinline__ void attn_step_fast(const LAS char* Kb, const LAS char* Vb, int lane, const bf16x8 (&qf)[2][2], const f32x4 negM, const bf16x8 onesf, f32x4 (&O)[2][8], f32x4 (&Oe)[2]) {
;     f32x4 s0[4], s1[4];
;     bf16x8 p0[2], p1[2];
;     {
;         bf16x8 kf[2][4][2];
; #pragma unroll
;         for (int c = 0; c < 2; ++c)
; #pragma unroll
;             for (int kb = 0; kb < 4; ++kb)
; #pragma unroll
;                 for (int ks = 0; ks < 2; ++ks) kf[c][kb][ks] = rowfrag(Kb, APIT, 16 * kb, c * 64 + 32 * ks, lane);
;         __builtin_amdgcn_sched_barrier(0);
; #pragma unroll
;         for (int kb = 0; kb < 4; ++kb) s0[kb] = mfma16(kf[0][kb][0], qf[0][0], negM);
; #pragma unroll
;         for (int kb = 0; kb < 4; ++kb) s0[kb] = mfma16(kf[0][kb][1], qf[0][1], s0[kb]);
;         __builtin_amdgcn_sched_barrier(0);
; #pragma unroll
;         for (int kb = 0; kb < 4; ++kb) s1[kb] = mfma16(kf[1][kb][0], qf[1][0], negM);
; #pragma unroll
;         for (int kb = 0; kb < 4; ++kb) s1[kb] = mfma16(kf[1][kb][1], qf[1][1], s1[kb]);
;     }
;     ...
;     ATT_EXPPACK(s0, p0);
; #pragma unroll
;     for (int i = 0; i < 8; ++i) { __builtin_amdgcn_sched_group_barrier(0x008, 1, 0); __builtin_amdgcn_sched_group_barrier(0x002, 3, 0); }
;     __builtin_amdgcn_sched_barrier(0);
;     bf16x8 va[8], vb[8];
; #pragma unroll
;     for (int nb = 0; nb < 8; ++nb) va[nb] = trfrag(Vb, APIT, 0, 16 * nb, lane);
; #pragma unroll
;     for (int nb = 0; nb < 8; ++nb) vb[nb] = trfrag(Vb, APIT, 32, 16 * nb, lane);
;     __builtin_amdgcn_sched_barrier(0);
;     Oe[0] = mfma16(onesf, p0[0], Oe[0]);
; #pragma unroll
;     for (int nb = 0; nb < 8; ++nb) O[0][nb] = mfma16(va[nb], p0[0], O[0][nb]);
;     Oe[0] = mfma16(onesf, p0[1], Oe[0]);
; #pragma unroll
;     for (int nb = 0; nb < 8; ++nb) O[0][nb] = mfma16(vb[nb], p0[1], O[0][nb]);
;     ATT_EXPPACK(s1, p1);
; #pragma unroll
;     for (int i = 0; i < 18; ++i) { __builtin_amdgcn_sched_group_barrier(0x008, 1, 0); __builtin_amdgcn_sched_group_barrier(0x002, 2, 0); }
;     __builtin_amdgcn_sched_barrier(0);
;     Oe[1] = mfma16(onesf, p1[0], Oe[1]);
; #pragma unroll
;     for (int nb = 0; nb < 8; ++nb) O[1][nb] = mfma16(va[nb], p1[0], O[1][nb]);
;     Oe[1] = mfma16(onesf, p1[1], Oe[1]);
; #pragma unroll
;     for (int nb = 0; nb < 8; ++nb) O[1][nb] = mfma16(vb[nb], p1[1], O[1][nb]);
.Lmy_attn_loop:
	s_cmp_eq_u32 s47, 1
	s_cbranch_scc1 .Lmy_attn_loop_m
	v_add_u32_e32 v181, s49, v230
	v_add_u32_e32 v205, s50, v231
	ds_read_b128 v[206:209], v181
	ds_read_b128 v[210:213], v181 offset:64
	ds_read_b128 v[214:217], v181 offset:4608
	ds_read_b128 v[218:221], v181 offset:4672
	ds_read_b128 v[222:225], v181 offset:9216
	v_lshl_add_u64 v[240:241], v[172:173], 0, s[4:5]
	global_load_dwordx4 v[146:149], v[240:241], off
	v_lshl_add_u64 v[240:241], v[172:173], 0, s[6:7]
	global_load_dwordx4 v[150:153], v[240:241], off
	v_lshl_add_u64 v[240:241], v[172:173], 0, s[8:9]
	global_load_dwordx4 v[154:157], v[240:241], off
	v_lshl_add_u64 v[240:241], v[172:173], 0, s[10:11]
	global_load_dwordx4 v[158:161], v[240:241], off
	v_lshl_add_u64 v[172:173], v[172:173], 0, s[76:77]
	v_cvt_pk_bf16_f32 v134, v106, v107
	v_cvt_pk_bf16_f32 v135, v108, v109
	v_cvt_pk_bf16_f32 v136, v110, v111
	v_cvt_pk_bf16_f32 v137, v112, v113
	v_cvt_pk_bf16_f32 v142, v122, v123
	v_cvt_pk_bf16_f32 v143, v124, v125
	v_cvt_pk_bf16_f32 v144, v126, v127
	v_cvt_pk_bf16_f32 v145, v128, v129
	s_waitcnt lgkmcnt(4)
	v_mfma_f32_16x16x32_bf16 v[98:101], v[206:209], v[34:37], v[2:5]
	v_mfma_f32_16x16x32_bf16 v[114:117], v[206:209], v[42:45], v[2:5]
	ds_read_b128 v[206:209], v181 offset:9280
	s_waitcnt lgkmcnt(4)
	v_mfma_f32_16x16x32_bf16 v[98:101], v[210:213], v[38:41], v[98:101]
	v_mfma_f32_16x16x32_bf16 v[114:117], v[210:213], v[50:53], v[114:117]
	ds_read_b128 v[210:213], v181 offset:13824
	s_waitcnt lgkmcnt(4)
	v_mfma_f32_16x16x32_bf16 v[102:105], v[214:217], v[34:37], v[2:5]
	v_mfma_f32_16x16x32_bf16 v[118:121], v[214:217], v[42:45], v[2:5]
	ds_read_b128 v[214:217], v181 offset:13888
	ds_read_b64_tr_b16 v[182:183], v205 offset:18432
	ds_read_b64_tr_b16 v[184:185], v205 offset:23040
	s_waitcnt lgkmcnt(6)
	v_mfma_f32_16x16x32_bf16 v[102:105], v[218:221], v[38:41], v[102:105]
	v_mfma_f32_16x16x32_bf16 v[118:121], v[218:221], v[50:53], v[118:121]
	ds_read_b64_tr_b16 v[186:187], v205 offset:18464
	ds_read_b64_tr_b16 v[188:189], v205 offset:23072
	s_waitcnt lgkmcnt(7)
	v_mfma_f32_16x16x32_bf16 v[106:109], v[222:225], v[34:37], v[2:5]
	v_mfma_f32_16x16x32_bf16 v[122:125], v[222:225], v[42:45], v[2:5]
	ds_read_b64_tr_b16 v[190:191], v205 offset:18496
	ds_read_b64_tr_b16 v[192:193], v205 offset:23104
	s_waitcnt lgkmcnt(8)
	v_mfma_f32_16x16x32_bf16 v[106:109], v[206:209], v[38:41], v[106:109]
	v_mfma_f32_16x16x32_bf16 v[122:125], v[206:209], v[50:53], v[122:125]
	ds_read_b64_tr_b16 v[226:227], v205 offset:18528
	ds_read_b64_tr_b16 v[228:229], v205 offset:23136
	s_waitcnt lgkmcnt(9)
	v_mfma_f32_16x16x32_bf16 v[110:113], v[210:213], v[34:37], v[2:5]
	v_mfma_f32_16x16x32_bf16 v[126:129], v[210:213], v[42:45], v[2:5]
	ds_read_b64_tr_b16 v[244:245], v205 offset:18560
	ds_read_b64_tr_b16 v[246:247], v205 offset:23168
	s_waitcnt lgkmcnt(10)
	v_mfma_f32_16x16x32_bf16 v[110:113], v[214:217], v[38:41], v[110:113]
	v_mfma_f32_16x16x32_bf16 v[126:129], v[214:217], v[50:53], v[126:129]
	ds_read_b64_tr_b16 v[248:249], v205 offset:18592
	ds_read_b64_tr_b16 v[250:251], v205 offset:23200
	v_add_u32_e32 v238, s50, v179
	v_add_u32_e32 v239, s49, v179
	v_mfma_f32_16x16x32_bf16 v[94:97], v[74:77], v[130:133], v[94:97]
	v_exp_f32_e32 v98, v98
	v_mfma_f32_16x16x32_bf16 v[90:93], v[74:77], v[138:141], v[90:93]
	v_exp_f32_e32 v99, v99
	s_waitcnt lgkmcnt(10)
	v_mfma_f32_16x16x32_bf16 v[82:85], v[182:185], v[130:133], v[82:85]
	v_exp_f32_e32 v100, v100
	v_mfma_f32_16x16x32_bf16 v[78:81], v[182:185], v[138:141], v[78:81]
	ds_read_b64_tr_b16 v[182:183], v205 offset:18624
	ds_read_b64_tr_b16 v[184:185], v205 offset:23232
	v_exp_f32_e32 v101, v101
	s_waitcnt lgkmcnt(10)
	v_mfma_f32_16x16x32_bf16 v[70:73], v[186:189], v[130:133], v[70:73]
	v_exp_f32_e32 v114, v114
	v_mfma_f32_16x16x32_bf16 v[62:65], v[186:189], v[138:141], v[62:65]
	ds_read_b64_tr_b16 v[186:187], v205 offset:18656
	ds_read_b64_tr_b16 v[188:189], v205 offset:23264
	v_exp_f32_e32 v115, v115
	s_waitcnt lgkmcnt(10)
	v_mfma_f32_16x16x32_bf16 v[58:61], v[190:193], v[130:133], v[58:61]
	v_exp_f32_e32 v116, v116
	v_mfma_f32_16x16x32_bf16 v[54:57], v[190:193], v[138:141], v[54:57]
	ds_read_b64_tr_b16 v[190:191], v205 offset:27648
	ds_read_b64_tr_b16 v[192:193], v205 offset:32256
	v_exp_f32_e32 v117, v117
	s_waitcnt lgkmcnt(10)
	v_mfma_f32_16x16x32_bf16 v[46:49], v[226:229], v[130:133], v[46:49]
	v_exp_f32_e32 v102, v102
	v_mfma_f32_16x16x32_bf16 v[30:33], v[226:229], v[138:141], v[30:33]
	ds_read_b64_tr_b16 v[226:227], v205 offset:27680
	ds_read_b64_tr_b16 v[228:229], v205 offset:32288
	v_exp_f32_e32 v103, v103
	s_waitcnt lgkmcnt(10)
	v_mfma_f32_16x16x32_bf16 v[26:29], v[244:247], v[130:133], v[26:29]
	v_exp_f32_e32 v104, v104
	v_mfma_f32_16x16x32_bf16 v[22:25], v[244:247], v[138:141], v[22:25]
	ds_read_b64_tr_b16 v[244:245], v205 offset:27712
	ds_read_b64_tr_b16 v[246:247], v205 offset:32320
	v_exp_f32_e32 v105, v105
	s_waitcnt lgkmcnt(10)
	v_mfma_f32_16x16x32_bf16 v[18:21], v[248:251], v[130:133], v[18:21]
	v_exp_f32_e32 v118, v118
	v_mfma_f32_16x16x32_bf16 v[14:17], v[248:251], v[138:141], v[14:17]
	ds_read_b64_tr_b16 v[248:249], v205 offset:27744
	ds_read_b64_tr_b16 v[250:251], v205 offset:32352
	v_exp_f32_e32 v119, v119
	s_waitcnt lgkmcnt(10)
	v_mfma_f32_16x16x32_bf16 v[6:9], v[182:185], v[130:133], v[6:9]
	v_exp_f32_e32 v120, v120
	v_mfma_f32_16x16x32_bf16 v[10:13], v[182:185], v[138:141], v[10:13]
	ds_read_b64_tr_b16 v[182:183], v205 offset:27776
	ds_read_b64_tr_b16 v[184:185], v205 offset:32384
	v_exp_f32_e32 v121, v121
	s_waitcnt lgkmcnt(10)
; __device__ __forceinline__ f32x4 mfma16(bf16x8 a, bf16x8 b, f32x4 c) { return __builtin_amdgcn_mfma_f32_16x16x32_bf16(a, b, c, 0, 0, 0); }
; __device__ __forceinline__ void attn_step_fast(const LAS char* Kb, const LAS char* Vb, int lane, const bf16x8 (&qf)[2][2], const f32x4 negM, const bf16x8 onesf, f32x4 (&O)[2][8], f32x4 (&Oe)[2]) {
;     ...
;     bf16x8 va[8], vb[8];
; #pragma unroll
;     for (int nb = 0; nb < 8; ++nb) va[nb] = trfrag(Vb, APIT, 0, 16 * nb, lane);
; #pragma unroll
;     for (int nb = 0; nb < 8; ++nb) vb[nb] = trfrag(Vb, APIT, 32, 16 * nb, lane);
;     __builtin_amdgcn_sched_barrier(0);
;     Oe[0] = mfma16(onesf, p0[0], Oe[0]);
; #pragma unroll
;     for (int nb = 0; nb < 8; ++nb) O[0][nb] = mfma16(va[nb], p0[0], O[0][nb]);
;     Oe[0] = mfma16(onesf, p0[1], Oe[0]);
; #pragma unroll
;     for (int nb = 0; nb < 8; ++nb) O[0][nb] = mfma16(vb[nb], p0[1], O[0][nb]);
;     ATT_EXPPACK(s1, p1);
; #pragma unroll
;     for (int i = 0; i < 18; ++i) { __builtin_amdgcn_sched_group_barrier(0x008, 1, 0); __builtin_amdgcn_sched_group_barrier(0x002, 2, 0); }
;     __builtin_amdgcn_sched_barrier(0);
;     Oe[1] = mfma16(onesf, p1[0], Oe[1]);
; #pragma unroll
;     for (int nb = 0; nb < 8; ++nb) O[1][nb] = mfma16(va[nb], p1[0], O[1][nb]);
;     Oe[1] = mfma16(onesf, p1[1], Oe[1]);
; #pragma unroll
;     for (int nb = 0; nb < 8; ++nb) O[1][nb] = mfma16(vb[nb], p1[1], O[1][nb]);
	v_mfma_f32_16x16x32_bf16 v[66:69], v[186:189], v[130:133], v[66:69]
	v_exp_f32_e32 v106, v106
	v_mfma_f32_16x16x32_bf16 v[86:89], v[186:189], v[138:141], v[86:89]
	ds_read_b64_tr_b16 v[186:187], v205 offset:27808
	ds_read_b64_tr_b16 v[188:189], v205 offset:32416
	v_exp_f32_e32 v107, v107
	v_mfma_f32_16x16x32_bf16 v[94:97], v[74:77], v[134:137], v[94:97]
	v_exp_f32_e32 v108, v108
	v_mfma_f32_16x16x32_bf16 v[90:93], v[74:77], v[142:145], v[90:93]
	v_exp_f32_e32 v109, v109
	s_waitcnt lgkmcnt(10)
	v_mfma_f32_16x16x32_bf16 v[82:85], v[190:193], v[134:137], v[82:85]
	v_exp_f32_e32 v122, v122
	v_mfma_f32_16x16x32_bf16 v[78:81], v[190:193], v[142:145], v[78:81]
	ds_read_b64_tr_b16 v[190:191], v205 offset:27840
	ds_read_b64_tr_b16 v[192:193], v205 offset:32448
	v_exp_f32_e32 v123, v123
	s_waitcnt lgkmcnt(10)
	v_mfma_f32_16x16x32_bf16 v[70:73], v[226:229], v[134:137], v[70:73]
	v_exp_f32_e32 v124, v124
	v_mfma_f32_16x16x32_bf16 v[62:65], v[226:229], v[142:145], v[62:65]
	ds_read_b64_tr_b16 v[226:227], v205 offset:27872
	ds_read_b64_tr_b16 v[228:229], v205 offset:32480
	v_exp_f32_e32 v125, v125
	s_waitcnt lgkmcnt(10)
	v_mfma_f32_16x16x32_bf16 v[58:61], v[244:247], v[134:137], v[58:61]
	v_exp_f32_e32 v110, v110
	v_mfma_f32_16x16x32_bf16 v[54:57], v[244:247], v[142:145], v[54:57]
	v_exp_f32_e32 v111, v111
	s_waitcnt lgkmcnt(8)
	v_mfma_f32_16x16x32_bf16 v[46:49], v[248:251], v[134:137], v[46:49]
	v_exp_f32_e32 v112, v112
	v_mfma_f32_16x16x32_bf16 v[30:33], v[248:251], v[142:145], v[30:33]
	v_exp_f32_e32 v113, v113
	s_waitcnt lgkmcnt(6)
	v_mfma_f32_16x16x32_bf16 v[26:29], v[182:185], v[134:137], v[26:29]
	v_exp_f32_e32 v126, v126
	s_waitcnt vmcnt(3)
	ds_write_b128 v238, v[146:149]
	v_mfma_f32_16x16x32_bf16 v[22:25], v[182:185], v[142:145], v[22:25]
	v_exp_f32_e32 v127, v127
	s_waitcnt lgkmcnt(5)
	v_mfma_f32_16x16x32_bf16 v[18:21], v[186:189], v[134:137], v[18:21]
	v_exp_f32_e32 v128, v128
	s_waitcnt vmcnt(2)
	ds_write_b128 v238, v[150:153] offset:9216
	v_mfma_f32_16x16x32_bf16 v[14:17], v[186:189], v[142:145], v[14:17]
	v_exp_f32_e32 v129, v129
	s_waitcnt lgkmcnt(4)
	v_mfma_f32_16x16x32_bf16 v[6:9], v[190:193], v[134:137], v[6:9]
	v_cvt_pk_bf16_f32 v130, v98, v99
	v_cvt_pk_bf16_f32 v131, v100, v101
	s_waitcnt vmcnt(1)
	ds_write_b128 v239, v[154:157] offset:18432
	v_mfma_f32_16x16x32_bf16 v[10:13], v[190:193], v[142:145], v[10:13]
	v_cvt_pk_bf16_f32 v132, v102, v103
	v_cvt_pk_bf16_f32 v133, v104, v105
	s_waitcnt lgkmcnt(3)
	v_mfma_f32_16x16x32_bf16 v[66:69], v[226:229], v[134:137], v[66:69]
	v_cvt_pk_bf16_f32 v138, v114, v115
	v_cvt_pk_bf16_f32 v139, v116, v117
	s_waitcnt vmcnt(0)
	ds_write_b128 v239, v[158:161] offset:27648
	v_mfma_f32_16x16x32_bf16 v[86:89], v[226:229], v[142:145], v[86:89]
	v_cvt_pk_bf16_f32 v140, v118, v119
	v_cvt_pk_bf16_f32 v141, v120, v121
	s_waitcnt lgkmcnt(0)
	s_barrier
	s_branch .Lmy_attn_next
.Lmy_attn_loop_m:
	v_add_u32_e32 v181, s49, v230
	v_add_u32_e32 v205, s50, v231
	ds_read_b128 v[206:209], v181
	ds_read_b128 v[210:213], v181 offset:64
	ds_read_b128 v[214:217], v181 offset:4608
	ds_read_b128 v[218:221], v181 offset:4672
	ds_read_b128 v[222:225], v181 offset:9216
	v_lshl_add_u64 v[240:241], v[172:173], 0, s[4:5]
	global_load_dwordx4 v[146:149], v[240:241], off
	v_lshl_add_u64 v[240:241], v[172:173], 0, s[6:7]
	global_load_dwordx4 v[150:153], v[240:241], off
	v_lshl_add_u64 v[240:241], v[172:173], 0, s[8:9]
	global_load_dwordx4 v[154:157], v[240:241], off
	v_lshl_add_u64 v[240:241], v[172:173], 0, s[10:11]
	global_load_dwordx4 v[158:161], v[240:241], off
	v_lshl_add_u64 v[172:173], v[172:173], 0, s[76:77]
	v_cvt_pk_bf16_f32 v134, v106, v107
	v_cvt_pk_bf16_f32 v135, v108, v109
	v_cvt_pk_bf16_f32 v136, v110, v111
	v_cvt_pk_bf16_f32 v137, v112, v113
	v_cvt_pk_bf16_f32 v142, v122, v123
	v_cvt_pk_bf16_f32 v143, v124, v125
	v_cvt_pk_bf16_f32 v144, v126, v127
	v_cvt_pk_bf16_f32 v145, v128, v129
	s_waitcnt lgkmcnt(4)
	v_mfma_f32_16x16x32_bf16 v[98:101], v[206:209], v[34:37], v[2:5]
	v_mfma_f32_16x16x32_bf16 v[114:117], v[206:209], v[42:45], v[2:5]
	ds_read_b128 v[206:209], v181 offset:9280
	s_waitcnt lgkmcnt(4)
	v_mfma_f32_16x16x32_bf16 v[98:101], v[210:213], v[38:41], v[98:101]
	v_mfma_f32_16x16x32_bf16 v[114:117], v[210:213], v[50:53], v[114:117]
	ds_read_b128 v[210:213], v181 offset:13824
	s_waitcnt lgkmcnt(4)
	v_mfma_f32_16x16x32_bf16 v[102:105], v[214:217], v[34:37], v[2:5]
	v_mfma_f32_16x16x32_bf16 v[118:121], v[214:217], v[42:45], v[2:5]
	ds_read_b128 v[214:217], v181 offset:13888
	ds_read_b64_tr_b16 v[182:183], v205 offset:18432
	ds_read_b64_tr_b16 v[184:185], v205 offset:23040
	s_waitcnt lgkmcnt(6)
	v_mfma_f32_16x16x32_bf16 v[102:105], v[218:221], v[38:41], v[102:105]
	v_mfma_f32_16x16x32_bf16 v[118:121], v[218:221], v[50:53], v[118:121]
	ds_read_b64_tr_b16 v[186:187], v205 offset:18464
	ds_read_b64_tr_b16 v[188:189], v205 offset:23072
	s_waitcnt lgkmcnt(7)
	v_mfma_f32_16x16x32_bf16 v[106:109], v[222:225], v[34:37], v[2:5]
	v_mfma_f32_16x16x32_bf16 v[122:125], v[222:225], v[42:45], v[2:5]
	ds_read_b64_tr_b16 v[190:191], v205 offset:18496
	ds_read_b64_tr_b16 v[192:193], v205 offset:23104
	s_waitcnt lgkmcnt(8)
	v_mfma_f32_16x16x32_bf16 v[106:109], v[206:209], v[38:41], v[106:109]
	v_mfma_f32_16x16x32_bf16 v[122:125], v[206:209], v[50:53], v[122:125]
	ds_read_b64_tr_b16 v[226:227], v205 offset:18528
	ds_read_b64_tr_b16 v[228:229], v205 offset:23136
	s_waitcnt lgkmcnt(9)
	v_mfma_f32_16x16x32_bf16 v[110:113], v[210:213], v[34:37], v[2:5]
	v_mfma_f32_16x16x32_bf16 v[126:129], v[210:213], v[42:45], v[2:5]
	ds_read_b64_tr_b16 v[244:245], v205 offset:18560
	ds_read_b64_tr_b16 v[246:247], v205 offset:23168
	s_waitcnt lgkmcnt(10)
; __device__ __forceinline__ unsigned cvt_pk_bf16(float lo, float hi) { const f32x2_t v = {lo, hi}; const bf16x2_t b = __builtin_convertvector(v, bf16x2_t); return __builtin_bit_cast(unsigned, b); }
; #define LAS __attribute__((address_space(3)))
; __device__ __forceinline__ f32x4 mfma16(bf16x8 a, bf16x8 b, f32x4 c) { return __builtin_amdgcn_mfma_f32_16x16x32_bf16(a, b, c, 0, 0, 0); }
; __device__ __forceinline__ void attn_qkexp(const LAS char* Kb, int k0, int q0, int wid, int lane, int g, int qpos, const bf16x8 (&qf)[2][2], const f32x4 negM, bf16x8 (&pf)[2][2]) {
;     ...
;     if (k0 + 63 > q0 + 16 * wid) {
; #pragma unroll
;         for (int c = 0; c < 2; ++c)
; #pragma unroll
;             for (int kb = 0; kb < 4; ++kb)
; #pragma unroll
;                 for (int r = 0; r < 4; ++r) if (k0 + 16 * kb + 4 * g + r > qpos) s[c][kb][r] = -INFINITY;
;     }
; #pragma unroll
;     for (int c = 0; c < 2; ++c) {
; #pragma unroll
;         for (int kb = 0; kb < 4; ++kb)
; #pragma unroll
;             for (int r = 0; r < 4; ++r) s[c][kb][r] = __builtin_amdgcn_exp2f(s[c][kb][r]);
; #pragma unroll
;         for (int tt = 0; tt < 2; ++tt) { u32x4 w; w.x = cvt_pk_bf16(s[c][2 * tt][0], s[c][2 * tt][1]); w.y = cvt_pk_bf16(s[c][2 * tt][2], s[c][2 * tt][3]);
;             w.z = cvt_pk_bf16(s[c][2 * tt + 1][0], s[c][2 * tt + 1][1]); w.w = cvt_pk_bf16(s[c][2 * tt + 1][2], s[c][2 * tt + 1][3]); pf[c][tt] = __builtin_bit_cast(bf16x8, w); }
;     }
; }
; __device__ __forceinline__ void attn_pv(const LAS char* Vb, int lane, const bf16x8 (&pf)[2][2], const bf16x8 onesf, f32x4 (&O)[2][8], f32x4 (&Oe)[2]) {
;     bf16x8 va[8], vb[8];
; #pragma unroll
;     for (int nb = 0; nb < 8; ++nb) va[nb] = trfrag(Vb, APIT, 0, 16 * nb, lane);
; #pragma unroll
;     for (int nb = 0; nb < 8; ++nb) vb[nb] = trfrag(Vb, APIT, 32, 16 * nb, lane);
;     __builtin_amdgcn_sched_barrier(0);
;     Oe[0] = mfma16(onesf, pf[0][0], Oe[0]); Oe[1] = mfma16(onesf, pf[1][0], Oe[1]);
; #pragma unroll
;     for (int nb = 0; nb < 8; ++nb) { O[0][nb] = mfma16(va[nb], pf[0][0], O[0][nb]); O[1][nb] = mfma16(va[nb], pf[1][0], O[1][nb]); }
;     Oe[0] = mfma16(onesf, pf[0][1], Oe[0]); Oe[1] = mfma16(onesf, pf[1][1], Oe[1]);
; #pragma unroll
;     for (int nb = 0; nb < 8; ++nb) { O[0][nb] = mfma16(vb[nb], pf[0][1], O[0][nb]); O[1][nb] = mfma16(vb[nb], pf[1][1], O[1][nb]); }
; }
	v_mfma_f32_16x16x32_bf16 v[110:113], v[214:217], v[38:41], v[110:113]
	v_mfma_f32_16x16x32_bf16 v[126:129], v[214:217], v[50:53], v[126:129]
	ds_read_b64_tr_b16 v[248:249], v205 offset:18592
	ds_read_b64_tr_b16 v[250:251], v205 offset:23200
	s_nop 7
	v_add_u32_e32 v240, 0, v243
	v_add_u32_e32 v241, 16, v243
	v_cmp_gt_i32_e64 s[12:13], 0, v240
	v_cmp_gt_i32_e64 s[14:15], 1, v240
	v_cmp_gt_i32_e64 s[16:17], 2, v240
	v_cmp_gt_i32_e64 s[18:19], 3, v240
	v_cndmask_b32_e64 v98, v98, v236, s[12:13]
	v_cmp_gt_i32_e64 s[20:21], 16, v240
	v_cndmask_b32_e64 v99, v99, v236, s[14:15]
	v_cmp_gt_i32_e64 s[22:23], 17, v240
	v_cndmask_b32_e64 v100, v100, v236, s[16:17]
	v_cmp_gt_i32_e64 s[24:25], 18, v240
	v_cndmask_b32_e64 v101, v101, v236, s[18:19]
	v_cmp_gt_i32_e64 s[26:27], 19, v240
	v_cndmask_b32_e64 v102, v102, v236, s[20:21]
	v_cmp_gt_i32_e64 s[28:29], 32, v240
	v_cndmask_b32_e64 v103, v103, v236, s[22:23]
	v_cmp_gt_i32_e64 s[30:31], 33, v240
	v_cndmask_b32_e64 v104, v104, v236, s[24:25]
	v_cmp_gt_i32_e64 s[12:13], 34, v240
	v_cndmask_b32_e64 v105, v105, v236, s[26:27]
	v_cmp_gt_i32_e64 s[14:15], 35, v240
	v_cndmask_b32_e64 v106, v106, v236, s[28:29]
	v_cmp_gt_i32_e64 s[16:17], 48, v240
	v_cndmask_b32_e64 v107, v107, v236, s[30:31]
	v_cmp_gt_i32_e64 s[18:19], 49, v240
	v_cndmask_b32_e64 v108, v108, v236, s[12:13]
	v_cmp_gt_i32_e64 s[20:21], 50, v240
	v_cndmask_b32_e64 v109, v109, v236, s[14:15]
	v_cmp_gt_i32_e64 s[22:23], 51, v240
	v_cndmask_b32_e64 v110, v110, v236, s[16:17]
	v_cmp_gt_i32_e64 s[24:25], 0, v241
	v_cndmask_b32_e64 v111, v111, v236, s[18:19]
	v_cmp_gt_i32_e64 s[26:27], 1, v241
	v_cndmask_b32_e64 v112, v112, v236, s[20:21]
	v_cmp_gt_i32_e64 s[28:29], 2, v241
	v_cndmask_b32_e64 v113, v113, v236, s[22:23]
	v_cmp_gt_i32_e64 s[30:31], 3, v241
	v_cndmask_b32_e64 v114, v114, v236, s[24:25]
	v_cmp_gt_i32_e64 s[12:13], 16, v241
	v_cndmask_b32_e64 v115, v115, v236, s[26:27]
	v_cmp_gt_i32_e64 s[14:15], 17, v241
	v_cndmask_b32_e64 v116, v116, v236, s[28:29]
	v_cmp_gt_i32_e64 s[16:17], 18, v241
	v_cndmask_b32_e64 v117, v117, v236, s[30:31]
	v_cmp_gt_i32_e64 s[18:19], 19, v241
	v_cndmask_b32_e64 v118, v118, v236, s[12:13]
	v_cmp_gt_i32_e64 s[20:21], 32, v241
	v_cndmask_b32_e64 v119, v119, v236, s[14:15]
	v_cmp_gt_i32_e64 s[22:23], 33, v241
	v_cndmask_b32_e64 v120, v120, v236, s[16:17]
	v_cmp_gt_i32_e64 s[24:25], 34, v241
	v_cndmask_b32_e64 v121, v121, v236, s[18:19]
	v_cmp_gt_i32_e64 s[26:27], 35, v241
	v_cndmask_b32_e64 v122, v122, v236, s[20:21]
	v_cmp_gt_i32_e64 s[28:29], 48, v241
	v_cndmask_b32_e64 v123, v123, v236, s[22:23]
	v_cmp_gt_i32_e64 s[30:31], 49, v241
	v_cndmask_b32_e64 v124, v124, v236, s[24:25]
	v_cmp_gt_i32_e64 s[12:13], 50, v241
	v_cndmask_b32_e64 v125, v125, v236, s[26:27]
	v_cmp_gt_i32_e64 s[14:15], 51, v241
	v_cndmask_b32_e64 v126, v126, v236, s[28:29]
	s_nop 1
	v_cndmask_b32_e64 v127, v127, v236, s[30:31]
	v_cndmask_b32_e64 v128, v128, v236, s[12:13]
	v_cndmask_b32_e64 v129, v129, v236, s[14:15]
	v_add_u32_e32 v238, s50, v179
	v_add_u32_e32 v239, s49, v179
	v_mfma_f32_16x16x32_bf16 v[94:97], v[74:77], v[130:133], v[94:97]
	v_exp_f32_e32 v98, v98
	v_mfma_f32_16x16x32_bf16 v[90:93], v[74:77], v[138:141], v[90:93]
	v_exp_f32_e32 v99, v99
	s_waitcnt lgkmcnt(10)
	v_mfma_f32_16x16x32_bf16 v[82:85], v[182:185], v[130:133], v[82:85]
	v_exp_f32_e32 v100, v100
	v_mfma_f32_16x16x32_bf16 v[78:81], v[182:185], v[138:141], v[78:81]
	ds_read_b64_tr_b16 v[182:183], v205 offset:18624
	ds_read_b64_tr_b16 v[184:185], v205 offset:23232
	v_exp_f32_e32 v101, v101
	s_waitcnt lgkmcnt(10)
	v_mfma_f32_16x16x32_bf16 v[70:73], v[186:189], v[130:133], v[70:73]
	v_exp_f32_e32 v114, v114
	v_mfma_f32_16x16x32_bf16 v[62:65], v[186:189], v[138:141], v[62:65]
	ds_read_b64_tr_b16 v[186:187], v205 offset:18656
	ds_read_b64_tr_b16 v[188:189], v205 offset:23264
	v_exp_f32_e32 v115, v115
	s_waitcnt lgkmcnt(10)
	v_mfma_f32_16x16x32_bf16 v[58:61], v[190:193], v[130:133], v[58:61]
	v_exp_f32_e32 v116, v116
	v_mfma_f32_16x16x32_bf16 v[54:57], v[190:193], v[138:141], v[54:57]
	ds_read_b64_tr_b16 v[190:191], v205 offset:27648
	ds_read_b64_tr_b16 v[192:193], v205 offset:32256
	v_exp_f32_e32 v117, v117
	s_waitcnt lgkmcnt(10)
	v_mfma_f32_16x16x32_bf16 v[46:49], v[226:229], v[130:133], v[46:49]
	v_exp_f32_e32 v102, v102
	v_mfma_f32_16x16x32_bf16 v[30:33], v[226:229], v[138:141], v[30:33]
	ds_read_b64_tr_b16 v[226:227], v205 offset:27680
	ds_read_b64_tr_b16 v[228:229], v205 offset:32288
	v_exp_f32_e32 v103, v103
	s_waitcnt lgkmcnt(10)
	v_mfma_f32_16x16x32_bf16 v[26:29], v[244:247], v[130:133], v[26:29]
	v_exp_f32_e32 v104, v104
	v_mfma_f32_16x16x32_bf16 v[22:25], v[244:247], v[138:141], v[22:25]
	ds_read_b64_tr_b16 v[244:245], v205 offset:27712
	ds_read_b64_tr_b16 v[246:247], v205 offset:32320
	v_exp_f32_e32 v105, v105
	s_waitcnt lgkmcnt(10)
	v_mfma_f32_16x16x32_bf16 v[18:21], v[248:251], v[130:133], v[18:21]
	v_exp_f32_e32 v118, v118
	v_mfma_f32_16x16x32_bf16 v[14:17], v[248:251], v[138:141], v[14:17]
	ds_read_b64_tr_b16 v[248:249], v205 offset:27744
	ds_read_b64_tr_b16 v[250:251], v205 offset:32352
	v_exp_f32_e32 v119, v119
	s_waitcnt lgkmcnt(10)
	v_mfma_f32_16x16x32_bf16 v[6:9], v[182:185], v[130:133], v[6:9]
	v_exp_f32_e32 v120, v120
	v_mfma_f32_16x16x32_bf16 v[10:13], v[182:185], v[138:141], v[10:13]
	ds_read_b64_tr_b16 v[182:183], v205 offset:27776
	ds_read_b64_tr_b16 v[184:185], v205 offset:32384
	v_exp_f32_e32 v121, v121
	s_waitcnt lgkmcnt(10)
; #define LAS __attribute__((address_space(3)))
; __device__ __forceinline__ f32x4 mfma16(bf16x8 a, bf16x8 b, f32x4 c) { return __builtin_amdgcn_mfma_f32_16x16x32_bf16(a, b, c, 0, 0, 0); }
; #define ATT_LOAD(tile) do { _Pragma("unroll") for (int i = 0; i < 2; ++i) { kr[i] = *(const u32x4*)(kg + (size_t)(64 * (tile) + 32 * i) * PP); vr[i] = *(const u32x4*)(vg + (size_t)(64 * (tile) + 32 * i) * PP); } } while (0)
; __device__ __forceinline__ void attn_step_fast(const LAS char* Kb, const LAS char* Vb, int lane, const bf16x8 (&qf)[2][2], const f32x4 negM, const bf16x8 onesf, f32x4 (&O)[2][8], f32x4 (&Oe)[2]) {
;     f32x4 s0[4], s1[4];
;     bf16x8 p0[2], p1[2];
;     {
;         bf16x8 kf[2][4][2];
; #pragma unroll
;         for (int c = 0; c < 2; ++c)
; #pragma unroll
;             for (int kb = 0; kb < 4; ++kb)
; #pragma unroll
;                 for (int ks = 0; ks < 2; ++ks) kf[c][kb][ks] = rowfrag(Kb, APIT, 16 * kb, c * 64 + 32 * ks, lane);
;         __builtin_amdgcn_sched_barrier(0);
; #pragma unroll
;         for (int kb = 0; kb < 4; ++kb) s0[kb] = mfma16(kf[0][kb][0], qf[0][0], negM);
; #pragma unroll
;         for (int kb = 0; kb < 4; ++kb) s0[kb] = mfma16(kf[0][kb][1], qf[0][1], s0[kb]);
;         __builtin_amdgcn_sched_barrier(0);
; #pragma unroll
;         for (int kb = 0; kb < 4; ++kb) s1[kb] = mfma16(kf[1][kb][0], qf[1][0], negM);
; #pragma unroll
;         for (int kb = 0; kb < 4; ++kb) s1[kb] = mfma16(kf[1][kb][1], qf[1][1], s1[kb]);
;     }
; __device__ __forceinline__ void attn_item(LAS char* lds, bf16_t* proj, int bl, int h, int qb, float lam, float oscale, const float* gdh, float smax) {
;     ...
;     for (; t < NT; ++t) {
;         const int k0 = 64 * t;
;         if (t + 1 < NT) ATT_LOAD(t + 1);
;         if (k0 <= qmaxw) {
;             const LAS char* Kb = lds + (t & 1) * ABUF;
;             attn_qkexp(Kb, k0, q0, wid, lane, g, qpos, qf, negM, pf);
;             attn_pv(Kb + ATILE, lane, pf, onesf, O, Oe);
	v_mfma_f32_16x16x32_bf16 v[66:69], v[186:189], v[130:133], v[66:69]
	v_exp_f32_e32 v106, v106
	v_mfma_f32_16x16x32_bf16 v[86:89], v[186:189], v[138:141], v[86:89]
	ds_read_b64_tr_b16 v[186:187], v205 offset:27808
	ds_read_b64_tr_b16 v[188:189], v205 offset:32416
	v_exp_f32_e32 v107, v107
	v_mfma_f32_16x16x32_bf16 v[94:97], v[74:77], v[134:137], v[94:97]
	v_exp_f32_e32 v108, v108
	v_mfma_f32_16x16x32_bf16 v[90:93], v[74:77], v[142:145], v[90:93]
	v_exp_f32_e32 v109, v109
	s_waitcnt lgkmcnt(10)
	v_mfma_f32_16x16x32_bf16 v[82:85], v[190:193], v[134:137], v[82:85]
	v_exp_f32_e32 v122, v122
	v_mfma_f32_16x16x32_bf16 v[78:81], v[190:193], v[142:145], v[78:81]
	ds_read_b64_tr_b16 v[190:191], v205 offset:27840
	ds_read_b64_tr_b16 v[192:193], v205 offset:32448
	v_exp_f32_e32 v123, v123
	s_waitcnt lgkmcnt(10)
	v_mfma_f32_16x16x32_bf16 v[70:73], v[226:229], v[134:137], v[70:73]
	v_exp_f32_e32 v124, v124
	v_mfma_f32_16x16x32_bf16 v[62:65], v[226:229], v[142:145], v[62:65]
	ds_read_b64_tr_b16 v[226:227], v205 offset:27872
	ds_read_b64_tr_b16 v[228:229], v205 offset:32480
	v_exp_f32_e32 v125, v125
	s_waitcnt lgkmcnt(10)
	v_mfma_f32_16x16x32_bf16 v[58:61], v[244:247], v[134:137], v[58:61]
	v_exp_f32_e32 v110, v110
	v_mfma_f32_16x16x32_bf16 v[54:57], v[244:247], v[142:145], v[54:57]
	v_exp_f32_e32 v111, v111
	s_waitcnt lgkmcnt(8)
	v_mfma_f32_16x16x32_bf16 v[46:49], v[248:251], v[134:137], v[46:49]
	v_exp_f32_e32 v112, v112
	v_mfma_f32_16x16x32_bf16 v[30:33], v[248:251], v[142:145], v[30:33]
	v_exp_f32_e32 v113, v113
	s_waitcnt lgkmcnt(6)
	v_mfma_f32_16x16x32_bf16 v[26:29], v[182:185], v[134:137], v[26:29]
	v_exp_f32_e32 v126, v126
	s_waitcnt vmcnt(3)
	ds_write_b128 v238, v[146:149]
	v_mfma_f32_16x16x32_bf16 v[22:25], v[182:185], v[142:145], v[22:25]
	v_exp_f32_e32 v127, v127
	s_waitcnt lgkmcnt(5)
	v_mfma_f32_16x16x32_bf16 v[18:21], v[186:189], v[134:137], v[18:21]
	v_exp_f32_e32 v128, v128
	s_waitcnt vmcnt(2)
	ds_write_b128 v238, v[150:153] offset:9216
	v_mfma_f32_16x16x32_bf16 v[14:17], v[186:189], v[142:145], v[14:17]
	v_exp_f32_e32 v129, v129
	s_waitcnt lgkmcnt(4)
	v_mfma_f32_16x16x32_bf16 v[6:9], v[190:193], v[134:137], v[6:9]
	v_cvt_pk_bf16_f32 v130, v98, v99
	v_cvt_pk_bf16_f32 v131, v100, v101
	s_waitcnt vmcnt(1)
	ds_write_b128 v239, v[154:157] offset:18432
	v_mfma_f32_16x16x32_bf16 v[10:13], v[190:193], v[142:145], v[10:13]
	v_cvt_pk_bf16_f32 v132, v102, v103
	v_cvt_pk_bf16_f32 v133, v104, v105
	s_waitcnt lgkmcnt(3)
	v_mfma_f32_16x16x32_bf16 v[66:69], v[226:229], v[134:137], v[66:69]
	v_cvt_pk_bf16_f32 v138, v114, v115
	v_cvt_pk_bf16_f32 v139, v116, v117
	s_waitcnt vmcnt(0)
	ds_write_b128 v239, v[158:161] offset:27648
	v_mfma_f32_16x16x32_bf16 v[86:89], v[226:229], v[142:145], v[86:89]
	v_cvt_pk_bf16_f32 v140, v118, v119
	v_cvt_pk_bf16_f32 v141, v120, v121
	s_waitcnt lgkmcnt(0)
	s_barrier
.Lmy_attn_next:
	s_xor_b32 s49, s49, 0x9000
	s_xor_b32 s50, s50, 0x9000
	s_add_i32 s47, s47, -1
	s_cmp_lg_u32 s47, 0
	s_cbranch_scc1 .Lmy_attn_loop
.Lmy_attn_last:
	v_add_u32_e32 v181, s49, v230
	v_add_u32_e32 v205, s50, v231
	ds_read_b128 v[206:209], v181
	ds_read_b128 v[210:213], v181 offset:64
	ds_read_b128 v[214:217], v181 offset:4608
	ds_read_b128 v[218:221], v181 offset:4672
	ds_read_b128 v[222:225], v181 offset:9216
	v_lshl_add_u64 v[240:241], v[172:173], 0, s[8:9]
	global_load_dwordx4 v[154:157], v[240:241], off
	v_lshl_add_u64 v[240:241], v[172:173], 0, s[10:11]
	global_load_dwordx4 v[158:161], v[240:241], off
	v_lshl_add_u64 v[172:173], v[172:173], 0, s[76:77]
	v_cvt_pk_bf16_f32 v134, v106, v107
	v_cvt_pk_bf16_f32 v135, v108, v109
	v_cvt_pk_bf16_f32 v136, v110, v111
	v_cvt_pk_bf16_f32 v137, v112, v113
	v_cvt_pk_bf16_f32 v142, v122, v123
	v_cvt_pk_bf16_f32 v143, v124, v125
	v_cvt_pk_bf16_f32 v144, v126, v127
	v_cvt_pk_bf16_f32 v145, v128, v129
	s_waitcnt lgkmcnt(4)
	v_mfma_f32_16x16x32_bf16 v[98:101], v[206:209], v[34:37], v[2:5]
	v_mfma_f32_16x16x32_bf16 v[114:117], v[206:209], v[42:45], v[2:5]
	ds_read_b128 v[206:209], v181 offset:9280
	s_waitcnt lgkmcnt(4)
	v_mfma_f32_16x16x32_bf16 v[98:101], v[210:213], v[38:41], v[98:101]
	v_mfma_f32_16x16x32_bf16 v[114:117], v[210:213], v[50:53], v[114:117]
	ds_read_b128 v[210:213], v181 offset:13824
	s_waitcnt lgkmcnt(4)
	v_mfma_f32_16x16x32_bf16 v[102:105], v[214:217], v[34:37], v[2:5]
	v_mfma_f32_16x16x32_bf16 v[118:121], v[214:217], v[42:45], v[2:5]
	ds_read_b128 v[214:217], v181 offset:13888
	ds_read_b64_tr_b16 v[182:183], v205 offset:18432
	ds_read_b64_tr_b16 v[184:185], v205 offset:23040
	s_waitcnt lgkmcnt(6)
	v_mfma_f32_16x16x32_bf16 v[102:105], v[218:221], v[38:41], v[102:105]
	v_mfma_f32_16x16x32_bf16 v[118:121], v[218:221], v[50:53], v[118:121]
	ds_read_b64_tr_b16 v[186:187], v205 offset:18464
	ds_read_b64_tr_b16 v[188:189], v205 offset:23072
	s_waitcnt lgkmcnt(7)
	v_mfma_f32_16x16x32_bf16 v[106:109], v[222:225], v[34:37], v[2:5]
	v_mfma_f32_16x16x32_bf16 v[122:125], v[222:225], v[42:45], v[2:5]
	ds_read_b64_tr_b16 v[190:191], v205 offset:18496
	ds_read_b64_tr_b16 v[192:193], v205 offset:23104
	s_waitcnt lgkmcnt(8)
	v_mfma_f32_16x16x32_bf16 v[106:109], v[206:209], v[38:41], v[106:109]
	v_mfma_f32_16x16x32_bf16 v[122:125], v[206:209], v[50:53], v[122:125]
	ds_read_b64_tr_b16 v[226:227], v205 offset:18528
	ds_read_b64_tr_b16 v[228:229], v205 offset:23136
	s_waitcnt lgkmcnt(9)
	v_mfma_f32_16x16x32_bf16 v[110:113], v[210:213], v[34:37], v[2:5]
	v_mfma_f32_16x16x32_bf16 v[126:129], v[210:213], v[42:45], v[2:5]
	ds_read_b64_tr_b16 v[244:245], v205 offset:18560
	ds_read_b64_tr_b16 v[246:247], v205 offset:23168
	s_waitcnt lgkmcnt(10)
; __device__ __forceinline__ unsigned cvt_pk_bf16(float lo, float hi) { const f32x2_t v = {lo, hi}; const bf16x2_t b = __builtin_convertvector(v, bf16x2_t); return __builtin_bit_cast(unsigned, b); }
; #define LAS __attribute__((address_space(3)))
; __device__ __forceinline__ f32x4 mfma16(bf16x8 a, bf16x8 b, f32x4 c) { return __builtin_amdgcn_mfma_f32_16x16x32_bf16(a, b, c, 0, 0, 0); }
; __device__ __forceinline__ void attn_qkexp(const LAS char* Kb, int k0, int q0, int wid, int lane, int g, int qpos, const bf16x8 (&qf)[2][2], const f32x4 negM, bf16x8 (&pf)[2][2]) {
;     ...
;     if (k0 + 63 > q0 + 16 * wid) {
; #pragma unroll
;         for (int c = 0; c < 2; ++c)
; #pragma unroll
;             for (int kb = 0; kb < 4; ++kb)
; #pragma unroll
;                 for (int r = 0; r < 4; ++r) if (k0 + 16 * kb + 4 * g + r > qpos) s[c][kb][r] = -INFINITY;
;     }
; #pragma unroll
;     for (int c = 0; c < 2; ++c) {
; #pragma unroll
;         for (int kb = 0; kb < 4; ++kb)
; #pragma unroll
;             for (int r = 0; r < 4; ++r) s[c][kb][r] = __builtin_amdgcn_exp2f(s[c][kb][r]);
; #pragma unroll
;         for (int tt = 0; tt < 2; ++tt) { u32x4 w; w.x = cvt_pk_bf16(s[c][2 * tt][0], s[c][2 * tt][1]); w.y = cvt_pk_bf16(s[c][2 * tt][2], s[c][2 * tt][3]);
;             w.z = cvt_pk_bf16(s[c][2 * tt + 1][0], s[c][2 * tt + 1][1]); w.w = cvt_pk_bf16(s[c][2 * tt + 1][2], s[c][2 * tt + 1][3]); pf[c][tt] = __builtin_bit_cast(bf16x8, w); }
;     }
; }
; __device__ __forceinline__ void attn_pv(const LAS char* Vb, int lane, const bf16x8 (&pf)[2][2], const bf16x8 onesf, f32x4 (&O)[2][8], f32x4 (&Oe)[2]) {
;     bf16x8 va[8], vb[8];
; #pragma unroll
;     for (int nb = 0; nb < 8; ++nb) va[nb] = trfrag(Vb, APIT, 0, 16 * nb, lane);
; #pragma unroll
;     for (int nb = 0; nb < 8; ++nb) vb[nb] = trfrag(Vb, APIT, 32, 16 * nb, lane);
;     __builtin_amdgcn_sched_barrier(0);
;     Oe[0] = mfma16(onesf, pf[0][0], Oe[0]); Oe[1] = mfma16(onesf, pf[1][0], Oe[1]);
; #pragma unroll
;     for (int nb = 0; nb < 8; ++nb) { O[0][nb] = mfma16(va[nb], pf[0][0], O[0][nb]); O[1][nb] = mfma16(va[nb], pf[1][0], O[1][nb]); }
;     Oe[0] = mfma16(onesf, pf[0][1], Oe[0]); Oe[1] = mfma16(onesf, pf[1][1], Oe[1]);
; #pragma unroll
;     for (int nb = 0; nb < 8; ++nb) { O[0][nb] = mfma16(vb[nb], pf[0][1], O[0][nb]); O[1][nb] = mfma16(vb[nb], pf[1][1], O[1][nb]); }
; }
	v_mfma_f32_16x16x32_bf16 v[110:113], v[214:217], v[38:41], v[110:113]
	v_mfma_f32_16x16x32_bf16 v[126:129], v[214:217], v[50:53], v[126:129]
	ds_read_b64_tr_b16 v[248:249], v205 offset:18592
	ds_read_b64_tr_b16 v[250:251], v205 offset:23200
	s_nop 7
	v_add_u32_e32 v240, -64, v243
	v_add_u32_e32 v241, -48, v243
	v_cmp_gt_i32_e64 s[12:13], 0, v240
	v_cmp_gt_i32_e64 s[14:15], 1, v240
	v_cmp_gt_i32_e64 s[16:17], 2, v240
	v_cmp_gt_i32_e64 s[18:19], 3, v240
	v_cndmask_b32_e64 v98, v98, v236, s[12:13]
	v_cmp_gt_i32_e64 s[20:21], 16, v240
	v_cndmask_b32_e64 v99, v99, v236, s[14:15]
	v_cmp_gt_i32_e64 s[22:23], 17, v240
	v_cndmask_b32_e64 v100, v100, v236, s[16:17]
	v_cmp_gt_i32_e64 s[24:25], 18, v240
	v_cndmask_b32_e64 v101, v101, v236, s[18:19]
	v_cmp_gt_i32_e64 s[26:27], 19, v240
	v_cndmask_b32_e64 v102, v102, v236, s[20:21]
	v_cmp_gt_i32_e64 s[28:29], 32, v240
	v_cndmask_b32_e64 v103, v103, v236, s[22:23]
	v_cmp_gt_i32_e64 s[30:31], 33, v240
	v_cndmask_b32_e64 v104, v104, v236, s[24:25]
	v_cmp_gt_i32_e64 s[12:13], 34, v240
	v_cndmask_b32_e64 v105, v105, v236, s[26:27]
	v_cmp_gt_i32_e64 s[14:15], 35, v240
	v_cndmask_b32_e64 v106, v106, v236, s[28:29]
	v_cmp_gt_i32_e64 s[16:17], 48, v240
	v_cndmask_b32_e64 v107, v107, v236, s[30:31]
	v_cmp_gt_i32_e64 s[18:19], 49, v240
	v_cndmask_b32_e64 v108, v108, v236, s[12:13]
	v_cmp_gt_i32_e64 s[20:21], 50, v240
	v_cndmask_b32_e64 v109, v109, v236, s[14:15]
	v_cmp_gt_i32_e64 s[22:23], 51, v240
	v_cndmask_b32_e64 v110, v110, v236, s[16:17]
	v_cmp_gt_i32_e64 s[24:25], 0, v241
	v_cndmask_b32_e64 v111, v111, v236, s[18:19]
	v_cmp_gt_i32_e64 s[26:27], 1, v241
	v_cndmask_b32_e64 v112, v112, v236, s[20:21]
	v_cmp_gt_i32_e64 s[28:29], 2, v241
	v_cndmask_b32_e64 v113, v113, v236, s[22:23]
	v_cmp_gt_i32_e64 s[30:31], 3, v241
	v_cndmask_b32_e64 v114, v114, v236, s[24:25]
	v_cmp_gt_i32_e64 s[12:13], 16, v241
	v_cndmask_b32_e64 v115, v115, v236, s[26:27]
	v_cmp_gt_i32_e64 s[14:15], 17, v241
	v_cndmask_b32_e64 v116, v116, v236, s[28:29]
	v_cmp_gt_i32_e64 s[16:17], 18, v241
	v_cndmask_b32_e64 v117, v117, v236, s[30:31]
	v_cmp_gt_i32_e64 s[18:19], 19, v241
	v_cndmask_b32_e64 v118, v118, v236, s[12:13]
	v_cmp_gt_i32_e64 s[20:21], 32, v241
	v_cndmask_b32_e64 v119, v119, v236, s[14:15]
	v_cmp_gt_i32_e64 s[22:23], 33, v241
	v_cndmask_b32_e64 v120, v120, v236, s[16:17]
	v_cmp_gt_i32_e64 s[24:25], 34, v241
	v_cndmask_b32_e64 v121, v121, v236, s[18:19]
	v_cmp_gt_i32_e64 s[26:27], 35, v241
	v_cndmask_b32_e64 v122, v122, v236, s[20:21]
	v_cmp_gt_i32_e64 s[28:29], 48, v241
	v_cndmask_b32_e64 v123, v123, v236, s[22:23]
	v_cmp_gt_i32_e64 s[30:31], 49, v241
	v_cndmask_b32_e64 v124, v124, v236, s[24:25]
	v_cmp_gt_i32_e64 s[12:13], 50, v241
	v_cndmask_b32_e64 v125, v125, v236, s[26:27]
	v_cmp_gt_i32_e64 s[14:15], 51, v241
	v_cndmask_b32_e64 v126, v126, v236, s[28:29]
	s_nop 1
	v_cndmask_b32_e64 v127, v127, v236, s[30:31]
	v_cndmask_b32_e64 v128, v128, v236, s[12:13]
	v_cndmask_b32_e64 v129, v129, v236, s[14:15]
	v_add_u32_e32 v238, s50, v179
	v_add_u32_e32 v239, s49, v179
	v_mfma_f32_16x16x32_bf16 v[94:97], v[74:77], v[130:133], v[94:97]
	v_exp_f32_e32 v98, v98
	v_mfma_f32_16x16x32_bf16 v[90:93], v[74:77], v[138:141], v[90:93]
	v_exp_f32_e32 v99, v99
	s_waitcnt lgkmcnt(10)
	v_mfma_f32_16x16x32_bf16 v[82:85], v[182:185], v[130:133], v[82:85]
	v_exp_f32_e32 v100, v100
	v_mfma_f32_16x16x32_bf16 v[78:81], v[182:185], v[138:141], v[78:81]
	ds_read_b64_tr_b16 v[182:183], v205 offset:18624
	ds_read_b64_tr_b16 v[184:185], v205 offset:23232
	v_exp_f32_e32 v101, v101
	s_waitcnt lgkmcnt(10)
	v_mfma_f32_16x16x32_bf16 v[70:73], v[186:189], v[130:133], v[70:73]
	v_exp_f32_e32 v114, v114
	v_mfma_f32_16x16x32_bf16 v[62:65], v[186:189], v[138:141], v[62:65]
	ds_read_b64_tr_b16 v[186:187], v205 offset:18656
	ds_read_b64_tr_b16 v[188:189], v205 offset:23264
	v_exp_f32_e32 v115, v115
	s_waitcnt lgkmcnt(10)
	v_mfma_f32_16x16x32_bf16 v[58:61], v[190:193], v[130:133], v[58:61]
	v_exp_f32_e32 v116, v116
	v_mfma_f32_16x16x32_bf16 v[54:57], v[190:193], v[138:141], v[54:57]
	ds_read_b64_tr_b16 v[190:191], v205 offset:27648
	ds_read_b64_tr_b16 v[192:193], v205 offset:32256
	v_exp_f32_e32 v117, v117
	s_waitcnt lgkmcnt(10)
	v_mfma_f32_16x16x32_bf16 v[46:49], v[226:229], v[130:133], v[46:49]
	v_exp_f32_e32 v102, v102
	v_mfma_f32_16x16x32_bf16 v[30:33], v[226:229], v[138:141], v[30:33]
	ds_read_b64_tr_b16 v[226:227], v205 offset:27680
	ds_read_b64_tr_b16 v[228:229], v205 offset:32288
	v_exp_f32_e32 v103, v103
	s_waitcnt lgkmcnt(10)
	v_mfma_f32_16x16x32_bf16 v[26:29], v[244:247], v[130:133], v[26:29]
	v_exp_f32_e32 v104, v104
	v_mfma_f32_16x16x32_bf16 v[22:25], v[244:247], v[138:141], v[22:25]
	ds_read_b64_tr_b16 v[244:245], v205 offset:27712
	ds_read_b64_tr_b16 v[246:247], v205 offset:32320
	v_exp_f32_e32 v105, v105
	s_waitcnt lgkmcnt(10)
	v_mfma_f32_16x16x32_bf16 v[18:21], v[248:251], v[130:133], v[18:21]
	v_exp_f32_e32 v118, v118
	v_mfma_f32_16x16x32_bf16 v[14:17], v[248:251], v[138:141], v[14:17]
	ds_read_b64_tr_b16 v[248:249], v205 offset:27744
	ds_read_b64_tr_b16 v[250:251], v205 offset:32352
	v_exp_f32_e32 v119, v119
	s_waitcnt lgkmcnt(10)
	v_mfma_f32_16x16x32_bf16 v[6:9], v[182:185], v[130:133], v[6:9]
	v_exp_f32_e32 v120, v120
	v_mfma_f32_16x16x32_bf16 v[10:13], v[182:185], v[138:141], v[10:13]
	ds_read_b64_tr_b16 v[182:183], v205 offset:27776
	ds_read_b64_tr_b16 v[184:185], v205 offset:32384
	v_exp_f32_e32 v121, v121
	s_waitcnt lgkmcnt(10)
; __device__ __forceinline__ f32x4 mfma16(bf16x8 a, bf16x8 b, f32x4 c) { return __builtin_amdgcn_mfma_f32_16x16x32_bf16(a, b, c, 0, 0, 0); }
; __device__ __forceinline__ void attn_step_fast(const LAS char* Kb, const LAS char* Vb, int lane, const bf16x8 (&qf)[2][2], const f32x4 negM, const bf16x8 onesf, f32x4 (&O)[2][8], f32x4 (&Oe)[2]) {
;     ...
;     Oe[0] = mfma16(onesf, p0[0], Oe[0]);
; #pragma unroll
;     for (int nb = 0; nb < 8; ++nb) O[0][nb] = mfma16(va[nb], p0[0], O[0][nb]);
;     Oe[0] = mfma16(onesf, p0[1], Oe[0]);
; #pragma unroll
;     for (int nb = 0; nb < 8; ++nb) O[0][nb] = mfma16(vb[nb], p0[1], O[0][nb]);
;     ATT_EXPPACK(s1, p1);
; #pragma unroll
;     for (int i = 0; i < 18; ++i) { __builtin_amdgcn_sched_group_barrier(0x008, 1, 0); __builtin_amdgcn_sched_group_barrier(0x002, 2, 0); }
;     __builtin_amdgcn_sched_barrier(0);
;     Oe[1] = mfma16(onesf, p1[0], Oe[1]);
; #pragma unroll
;     for (int nb = 0; nb < 8; ++nb) O[1][nb] = mfma16(va[nb], p1[0], O[1][nb]);
;     Oe[1] = mfma16(onesf, p1[1], Oe[1]);
; #pragma unroll
;     for (int nb = 0; nb < 8; ++nb) O[1][nb] = mfma16(vb[nb], p1[1], O[1][nb]);
	v_mfma_f32_16x16x32_bf16 v[66:69], v[186:189], v[130:133], v[66:69]
	v_exp_f32_e32 v106, v106
	v_mfma_f32_16x16x32_bf16 v[86:89], v[186:189], v[138:141], v[86:89]
	ds_read_b64_tr_b16 v[186:187], v205 offset:27808
	ds_read_b64_tr_b16 v[188:189], v205 offset:32416
	v_exp_f32_e32 v107, v107
	v_mfma_f32_16x16x32_bf16 v[94:97], v[74:77], v[134:137], v[94:97]
	v_exp_f32_e32 v108, v108
	v_mfma_f32_16x16x32_bf16 v[90:93], v[74:77], v[142:145], v[90:93]
	v_exp_f32_e32 v109, v109
	s_waitcnt lgkmcnt(10)
	v_mfma_f32_16x16x32_bf16 v[82:85], v[190:193], v[134:137], v[82:85]
	v_exp_f32_e32 v122, v122
	v_mfma_f32_16x16x32_bf16 v[78:81], v[190:193], v[142:145], v[78:81]
	ds_read_b64_tr_b16 v[190:191], v205 offset:27840
	ds_read_b64_tr_b16 v[192:193], v205 offset:32448
	v_exp_f32_e32 v123, v123
	s_waitcnt lgkmcnt(10)
	v_mfma_f32_16x16x32_bf16 v[70:73], v[226:229], v[134:137], v[70:73]
	v_exp_f32_e32 v124, v124
	v_mfma_f32_16x16x32_bf16 v[62:65], v[226:229], v[142:145], v[62:65]
	ds_read_b64_tr_b16 v[226:227], v205 offset:27872
	ds_read_b64_tr_b16 v[228:229], v205 offset:32480
	v_exp_f32_e32 v125, v125
	s_waitcnt lgkmcnt(10)
	v_mfma_f32_16x16x32_bf16 v[58:61], v[244:247], v[134:137], v[58:61]
	v_exp_f32_e32 v110, v110
	v_mfma_f32_16x16x32_bf16 v[54:57], v[244:247], v[142:145], v[54:57]
	v_exp_f32_e32 v111, v111
	s_waitcnt lgkmcnt(8)
	v_mfma_f32_16x16x32_bf16 v[46:49], v[248:251], v[134:137], v[46:49]
	v_exp_f32_e32 v112, v112
	v_mfma_f32_16x16x32_bf16 v[30:33], v[248:251], v[142:145], v[30:33]
	v_exp_f32_e32 v113, v113
	s_waitcnt lgkmcnt(6)
	v_mfma_f32_16x16x32_bf16 v[26:29], v[182:185], v[134:137], v[26:29]
	v_exp_f32_e32 v126, v126
	s_waitcnt vmcnt(1)
	ds_write_b128 v239, v[154:157] offset:18432
	v_mfma_f32_16x16x32_bf16 v[22:25], v[182:185], v[142:145], v[22:25]
	v_exp_f32_e32 v127, v127
	s_waitcnt lgkmcnt(5)
	v_mfma_f32_16x16x32_bf16 v[18:21], v[186:189], v[134:137], v[18:21]
	v_exp_f32_e32 v128, v128
	s_waitcnt vmcnt(0)
	ds_write_b128 v239, v[158:161] offset:27648
	v_mfma_f32_16x16x32_bf16 v[14:17], v[186:189], v[142:145], v[14:17]
	v_exp_f32_e32 v129, v129
	s_waitcnt lgkmcnt(4)
	v_mfma_f32_16x16x32_bf16 v[6:9], v[190:193], v[134:137], v[6:9]
	v_cvt_pk_bf16_f32 v130, v98, v99
	v_cvt_pk_bf16_f32 v131, v100, v101
	v_mfma_f32_16x16x32_bf16 v[10:13], v[190:193], v[142:145], v[10:13]
	v_cvt_pk_bf16_f32 v132, v102, v103
	v_cvt_pk_bf16_f32 v133, v104, v105
	s_waitcnt lgkmcnt(2)
	v_mfma_f32_16x16x32_bf16 v[66:69], v[226:229], v[134:137], v[66:69]
	v_cvt_pk_bf16_f32 v138, v114, v115
	v_cvt_pk_bf16_f32 v139, v116, v117
	v_mfma_f32_16x16x32_bf16 v[86:89], v[226:229], v[142:145], v[86:89]
	v_cvt_pk_bf16_f32 v140, v118, v119
	v_cvt_pk_bf16_f32 v141, v120, v121
	s_waitcnt lgkmcnt(0)
	s_barrier
; #define LAS __attribute__((address_space(3)))
; __device__ __forceinline__ f32x4 mfma16(bf16x8 a, bf16x8 b, f32x4 c) { return __builtin_amdgcn_mfma_f32_16x16x32_bf16(a, b, c, 0, 0, 0); }
; __device__ __forceinline__ void attn_pv(const LAS char* Vb, int lane, const bf16x8 (&pf)[2][2], const bf16x8 onesf, f32x4 (&O)[2][8], f32x4 (&Oe)[2]) {
;     bf16x8 va[8], vb[8];
; #pragma unroll
;     for (int nb = 0; nb < 8; ++nb) va[nb] = trfrag(Vb, APIT, 0, 16 * nb, lane);
; #pragma unroll
;     for (int nb = 0; nb < 8; ++nb) vb[nb] = trfrag(Vb, APIT, 32, 16 * nb, lane);
;     __builtin_amdgcn_sched_barrier(0);
;     Oe[0] = mfma16(onesf, pf[0][0], Oe[0]); Oe[1] = mfma16(onesf, pf[1][0], Oe[1]);
; #pragma unroll
;     for (int nb = 0; nb < 8; ++nb) { O[0][nb] = mfma16(va[nb], pf[0][0], O[0][nb]); O[1][nb] = mfma16(va[nb], pf[1][0], O[1][nb]); }
;     Oe[0] = mfma16(onesf, pf[0][1], Oe[0]); Oe[1] = mfma16(onesf, pf[1][1], Oe[1]);
; #pragma unroll
;     for (int nb = 0; nb < 8; ++nb) { O[0][nb] = mfma16(vb[nb], pf[0][1], O[0][nb]); O[1][nb] = mfma16(vb[nb], pf[1][1], O[1][nb]); }
; }
; __device__ __forceinline__ void attn_item(LAS char* lds, bf16_t* proj, int bl, int h, int qb, float lam, float oscale, const float* gdh, float smax) {
;     ...
;     const float l0 = __shfl(Oe[0][0], fr), l1 = __shfl(Oe[1][0], fr);
;     const float r0 = 1.0f / l0, r1 = lam / l1;
;     float ss = 0.f;
; #pragma unroll
;     for (int nb = 0; nb < 8; ++nb)
; #pragma unroll
;         for (int r = 0; r < 4; ++r) { const float o = O[0][nb][r] * r0 - O[1][nb][r] * r1; O[0][nb][r] = o; ss += o * o; }
	s_xor_b32 s49, s49, 0x9000
	s_xor_b32 s50, s50, 0x9000
	v_add_u32_e32 v181, s49, v230
	v_add_u32_e32 v205, s50, v231
	v_cvt_pk_bf16_f32 v134, v106, v107
	v_cvt_pk_bf16_f32 v135, v108, v109
	v_cvt_pk_bf16_f32 v136, v110, v111
	v_cvt_pk_bf16_f32 v137, v112, v113
	v_cvt_pk_bf16_f32 v142, v122, v123
	v_cvt_pk_bf16_f32 v143, v124, v125
	v_cvt_pk_bf16_f32 v144, v126, v127
	v_cvt_pk_bf16_f32 v145, v128, v129
	ds_read_b64_tr_b16 v[182:183], v205 offset:18432
	ds_read_b64_tr_b16 v[184:185], v205 offset:23040
	ds_read_b64_tr_b16 v[186:187], v205 offset:18464
	ds_read_b64_tr_b16 v[188:189], v205 offset:23072
	ds_read_b64_tr_b16 v[190:191], v205 offset:18496
	ds_read_b64_tr_b16 v[192:193], v205 offset:23104
	ds_read_b64_tr_b16 v[226:227], v205 offset:18528
	ds_read_b64_tr_b16 v[228:229], v205 offset:23136
	ds_read_b64_tr_b16 v[244:245], v205 offset:18560
	ds_read_b64_tr_b16 v[246:247], v205 offset:23168
	ds_read_b64_tr_b16 v[248:249], v205 offset:18592
	ds_read_b64_tr_b16 v[250:251], v205 offset:23200
	v_add_u32_e32 v238, s50, v179
	v_add_u32_e32 v239, s49, v179
	v_mfma_f32_16x16x32_bf16 v[94:97], v[74:77], v[130:133], v[94:97]
	v_mfma_f32_16x16x32_bf16 v[90:93], v[74:77], v[138:141], v[90:93]
	s_waitcnt lgkmcnt(10)
	v_mfma_f32_16x16x32_bf16 v[82:85], v[182:185], v[130:133], v[82:85]
	v_mfma_f32_16x16x32_bf16 v[78:81], v[182:185], v[138:141], v[78:81]
	ds_read_b64_tr_b16 v[182:183], v205 offset:18624
	ds_read_b64_tr_b16 v[184:185], v205 offset:23232
	s_waitcnt lgkmcnt(10)
	v_mfma_f32_16x16x32_bf16 v[70:73], v[186:189], v[130:133], v[70:73]
	v_mfma_f32_16x16x32_bf16 v[62:65], v[186:189], v[138:141], v[62:65]
	ds_read_b64_tr_b16 v[186:187], v205 offset:18656
	ds_read_b64_tr_b16 v[188:189], v205 offset:23264
	s_waitcnt lgkmcnt(10)
	v_mfma_f32_16x16x32_bf16 v[58:61], v[190:193], v[130:133], v[58:61]
	v_mfma_f32_16x16x32_bf16 v[54:57], v[190:193], v[138:141], v[54:57]
	ds_read_b64_tr_b16 v[190:191], v205 offset:27648
	ds_read_b64_tr_b16 v[192:193], v205 offset:32256
	s_waitcnt lgkmcnt(10)
	v_mfma_f32_16x16x32_bf16 v[46:49], v[226:229], v[130:133], v[46:49]
	v_mfma_f32_16x16x32_bf16 v[30:33], v[226:229], v[138:141], v[30:33]
	ds_read_b64_tr_b16 v[226:227], v205 offset:27680
	ds_read_b64_tr_b16 v[228:229], v205 offset:32288
	s_waitcnt lgkmcnt(10)
	v_mfma_f32_16x16x32_bf16 v[26:29], v[244:247], v[130:133], v[26:29]
	v_mfma_f32_16x16x32_bf16 v[22:25], v[244:247], v[138:141], v[22:25]
	ds_read_b64_tr_b16 v[244:245], v205 offset:27712
	ds_read_b64_tr_b16 v[246:247], v205 offset:32320
	s_waitcnt lgkmcnt(10)
	v_mfma_f32_16x16x32_bf16 v[18:21], v[248:251], v[130:133], v[18:21]
	v_mfma_f32_16x16x32_bf16 v[14:17], v[248:251], v[138:141], v[14:17]
	ds_read_b64_tr_b16 v[248:249], v205 offset:27744
	ds_read_b64_tr_b16 v[250:251], v205 offset:32352
	s_waitcnt lgkmcnt(10)
	v_mfma_f32_16x16x32_bf16 v[6:9], v[182:185], v[130:133], v[6:9]
	v_mfma_f32_16x16x32_bf16 v[10:13], v[182:185], v[138:141], v[10:13]
	ds_read_b64_tr_b16 v[182:183], v205 offset:27776
	ds_read_b64_tr_b16 v[184:185], v205 offset:32384
	s_waitcnt lgkmcnt(10)
	v_mfma_f32_16x16x32_bf16 v[66:69], v[186:189], v[130:133], v[66:69]
	v_mfma_f32_16x16x32_bf16 v[86:89], v[186:189], v[138:141], v[86:89]
	ds_read_b64_tr_b16 v[186:187], v205 offset:27808
	ds_read_b64_tr_b16 v[188:189], v205 offset:32416
	v_mfma_f32_16x16x32_bf16 v[94:97], v[74:77], v[134:137], v[94:97]
	v_mfma_f32_16x16x32_bf16 v[90:93], v[74:77], v[142:145], v[90:93]
	s_waitcnt lgkmcnt(10)
	v_mfma_f32_16x16x32_bf16 v[82:85], v[190:193], v[134:137], v[82:85]
	v_mfma_f32_16x16x32_bf16 v[78:81], v[190:193], v[142:145], v[78:81]
	ds_read_b64_tr_b16 v[190:191], v205 offset:27840
	ds_read_b64_tr_b16 v[192:193], v205 offset:32448
	s_waitcnt lgkmcnt(10)
	v_mfma_f32_16x16x32_bf16 v[70:73], v[226:229], v[134:137], v[70:73]
	v_mfma_f32_16x16x32_bf16 v[62:65], v[226:229], v[142:145], v[62:65]
	ds_read_b64_tr_b16 v[226:227], v205 offset:27872
	ds_read_b64_tr_b16 v[228:229], v205 offset:32480
	s_waitcnt lgkmcnt(10)
	v_mfma_f32_16x16x32_bf16 v[58:61], v[244:247], v[134:137], v[58:61]
	v_mfma_f32_16x16x32_bf16 v[54:57], v[244:247], v[142:145], v[54:57]
	s_waitcnt lgkmcnt(8)
	v_mfma_f32_16x16x32_bf16 v[46:49], v[248:251], v[134:137], v[46:49]
	v_mfma_f32_16x16x32_bf16 v[30:33], v[248:251], v[142:145], v[30:33]
	s_waitcnt lgkmcnt(6)
	v_mfma_f32_16x16x32_bf16 v[26:29], v[182:185], v[134:137], v[26:29]
	v_mfma_f32_16x16x32_bf16 v[22:25], v[182:185], v[142:145], v[22:25]
	s_waitcnt lgkmcnt(4)
	v_mfma_f32_16x16x32_bf16 v[18:21], v[186:189], v[134:137], v[18:21]
	v_mfma_f32_16x16x32_bf16 v[14:17], v[186:189], v[142:145], v[14:17]
	s_waitcnt lgkmcnt(2)
	v_mfma_f32_16x16x32_bf16 v[6:9], v[190:193], v[134:137], v[6:9]
	v_mfma_f32_16x16x32_bf16 v[10:13], v[190:193], v[142:145], v[10:13]
	s_waitcnt lgkmcnt(0)
	v_mfma_f32_16x16x32_bf16 v[66:69], v[226:229], v[134:137], v[66:69]
	v_mfma_f32_16x16x32_bf16 v[86:89], v[226:229], v[142:145], v[86:89]
	s_waitcnt lgkmcnt(0)
	s_barrier
	s_nop 7
	v_readfirstlane_b32 s0, v194
	s_nop 3
	s_lshr_b32 s0, s0, 6
	s_mul_i32 s1, s0, 0x2400
	v_lshlrev_b32_e32 v240, 4, v235
	v_add_u32_e32 v241, s1, v240
	s_xor_b32 s0, s0, 1
	s_mul_i32 s1, s0, 0x2400
	v_add_u32_e32 v240, s1, v240
	s_cmp_eq_u32 s48, 0
	s_cbranch_scc0 .Lmy_x_send0
	ds_write_b128 v241, v[78:81]
	ds_write_b128 v241, v[62:65] offset:1024
	ds_write_b128 v241, v[54:57] offset:2048
	ds_write_b128 v241, v[30:33] offset:3072
	ds_write_b128 v241, v[22:25] offset:4096
	ds_write_b128 v241, v[14:17] offset:5120
	ds_write_b128 v241, v[10:13] offset:6144
	ds_write_b128 v241, v[86:89] offset:7168
	ds_write_b128 v241, v[90:93] offset:8192
	s_branch .Lmy_x_sent
.Lmy_x_send0:
	ds_write_b128 v241, v[82:85]
	ds_write_b128 v241, v[70:73] offset:1024
	ds_write_b128 v241, v[58:61] offset:2048
	ds_write_b128 v241, v[46:49] offset:3072
	ds_write_b128 v241, v[26:29] offset:4096
	ds_write_b128 v241, v[18:21] offset:5120
	ds_write_b128 v241, v[6:9] offset:6144
	ds_write_b128 v241, v[66:69] offset:7168
	ds_write_b128 v241, v[94:97] offset:8192
.Lmy_x_sent:
	s_waitcnt lgkmcnt(0)
	s_barrier
	s_cmp_eq_u32 s48, 0
	s_cbranch_scc0 .Lmy_x_recv0
	ds_read_b128 v[78:81], v240
	ds_read_b128 v[62:65], v240 offset:1024
	ds_read_b128 v[54:57], v240 offset:2048
	ds_read_b128 v[30:33], v240 offset:3072
	ds_read_b128 v[22:25], v240 offset:4096
	ds_read_b128 v[14:17], v240 offset:5120
	ds_read_b128 v[10:13], v240 offset:6144
	ds_read_b128 v[86:89], v240 offset:7168
	ds_read_b128 v[90:93], v240 offset:8192
	s_branch .Lmy_x_done
.Lmy_x_recv0:
	ds_read_b128 v[82:85], v240
	ds_read_b128 v[70:73], v240 offset:1024
	ds_read_b128 v[58:61], v240 offset:2048
	ds_read_b128 v[46:49], v240 offset:3072
	ds_read_b128 v[26:29], v240 offset:4096
	ds_read_b128 v[18:21], v240 offset:5120
	ds_read_b128 v[6:9], v240 offset:6144
	ds_read_b128 v[66:69], v240 offset:7168
	ds_read_b128 v[94:97], v240 offset:8192
.Lmy_x_done:
	s_waitcnt lgkmcnt(0)
	s_barrier
	s_movk_i32 s49, 0x7fff
	s_mov_b32 s50, 0xf800000
	s_branch .LBB0_240
